# v7max3
# speedup vs baseline: 1.0491x; 1.0195x over previous
; __device__ __forceinline__ void finishSM(f32x16& p0, f32x16& p1, float alpha, float& l_reg, bf16x8& pa0, bf16x8& pa1, bf16x8& pa2, bf16x8& pa3) {
; #pragma unroll
;     for (int r = 0; r < 16; ++r) p1[r] = __builtin_amdgcn_exp2f(p1[r]);
;     float ps = 0;
; #pragma unroll
;     for (int r = 0; r < 16; ++r) ps += p0[r];
; #pragma unroll
;     for (int r = 0; r < 16; ++r) ps += p1[r];
;     { auto rr = __builtin_amdgcn_permlane32_swap(__float_as_uint(ps), __float_as_uint(ps), false, false);
;       ps = __uint_as_float(rr[0]) + __uint_as_float(rr[1]); }
;     l_reg = l_reg * alpha + ps;
;     PK4(p0, 0, pa0); PK4(p0, 8, pa1); PK4(p1, 0, pa2); PK4(p1, 8, pa3);
; }
; __device__ __forceinline__ void pv_tile(f32x16* o, int vb0, bf16x8 pa0, bf16x8 pa1, bf16x8 pa2, bf16x8 pa3) {
;     ...
;     PV_D0(0); PV_D0(1); PV_D0(2); PV_D0(3);
;     ...
; }
.LBB0_323:
	v_add_f32_e32 v2, 0, v243
	v_add_f32_e32 v2, v242, v2
	v_add_f32_e32 v2, v241, v2
	v_add_f32_e32 v2, v240, v2
	v_add_f32_e32 v2, v239, v2
	v_add_f32_e32 v2, v238, v2
	v_add_f32_e32 v2, v237, v2
	v_add_f32_e32 v2, v236, v2
	v_add_f32_e32 v2, v235, v2
	v_add_f32_e32 v2, v234, v2
	v_add_f32_e32 v2, v233, v2
	v_add_f32_e32 v2, v232, v2
	v_exp_f32_e32 v10, v14
	v_add_f32_e32 v2, v231, v2
	v_exp_f32_e32 v11, v15
	v_add_f32_e32 v2, v230, v2
	v_exp_f32_e32 v12, v176
	v_add_f32_e32 v2, v216, v2
	v_exp_f32_e32 v13, v177
	v_add_f32_e32 v2, v179, v2
	v_exp_f32_e32 v14, v116
	v_add_f32_e32 v2, v10, v2
	v_exp_f32_e32 v15, v117
	v_add_f32_e32 v2, v11, v2
	v_exp_f32_e32 v80, v118
	v_add_f32_e32 v2, v12, v2
	v_exp_f32_e32 v81, v119
	v_add_f32_e32 v2, v13, v2
	v_exp_f32_e32 v82, v120
	v_add_f32_e32 v2, v14, v2
	v_exp_f32_e32 v83, v121
	v_add_f32_e32 v2, v15, v2
	v_exp_f32_e32 v84, v122
	v_add_f32_e32 v2, v80, v2
	v_exp_f32_e32 v85, v123
	v_add_f32_e32 v2, v81, v2
	v_exp_f32_e32 v86, v124
	v_add_f32_e32 v2, v82, v2
	v_exp_f32_e32 v87, v125
	v_add_f32_e32 v2, v83, v2
	v_exp_f32_e32 v88, v126
	v_add_f32_e32 v2, v84, v2
	v_exp_f32_e32 v89, v127
	v_add_f32_e32 v2, v85, v2
	v_add_f32_e32 v2, v86, v2
	v_add_f32_e32 v2, v87, v2
	v_add_f32_e32 v2, v88, v2
	v_add_f32_e32 v2, v89, v2
	v_mov_b32_e32 v3, v2
	s_nop 1
	v_permlane32_swap_b32_e32 v2, v3
	v_add_f32_e32 v2, v2, v3
	s_add_i32 s0, 0, 0xc000
	v_add_f32_e32 v0, v0, v2
	v_cvt_pk_bf16_f32 v2, v243, v242
	v_cvt_pk_bf16_f32 v3, v241, v240
	v_cvt_pk_bf16_f32 v4, v239, v238
	v_cvt_pk_bf16_f32 v5, v237, v236
	v_cvt_pk_bf16_f32 v6, v235, v234
	v_cvt_pk_bf16_f32 v7, v233, v232
	v_cvt_pk_bf16_f32 v8, v231, v230
	v_cvt_pk_bf16_f32 v9, v216, v179
	v_cvt_pk_bf16_f32 v10, v10, v11
	v_cvt_pk_bf16_f32 v11, v12, v13
	v_cvt_pk_bf16_f32 v12, v14, v15
	v_cvt_pk_bf16_f32 v13, v80, v81
	v_cvt_pk_bf16_f32 v80, v82, v83
	v_cvt_pk_bf16_f32 v81, v84, v85
	v_cvt_pk_bf16_f32 v82, v86, v87
	v_cvt_pk_bf16_f32 v83, v88, v89
	v_add_u32_e32 v14, s0, v218
	ds_read_b64_tr_b16 v[84:85], v14 offset:0
	ds_read_b64_tr_b16 v[86:87], v14 offset:0x800
	ds_read_b64_tr_b16 v[88:89], v14 offset:0x1000
	ds_read_b64_tr_b16 v[90:91], v14 offset:0x1800
	ds_read_b64_tr_b16 v[92:93], v14 offset:0x2000
	ds_read_b64_tr_b16 v[94:95], v14 offset:0x2800
	ds_read_b64_tr_b16 v[96:97], v14 offset:0x3000
	v_permlane32_swap_b32_e32 v2, v4
	v_permlane32_swap_b32_e32 v3, v5
	ds_read_b64_tr_b16 v[98:99], v14 offset:0x3800
	v_permlane32_swap_b32_e32 v6, v8
	s_waitcnt lgkmcnt(0)
	v_permlane32_swap_b32_e32 v7, v9
	v_mfma_f32_32x32x16_bf16 v[64:79], v[84:87], v[2:5], v[64:79]
	v_permlane32_swap_b32_e32 v10, v12
	v_permlane32_swap_b32_e32 v11, v13
	ds_read_b64_tr_b16 v[84:85], v14 offset:0x200
	ds_read_b64_tr_b16 v[86:87], v14 offset:0xa00
	v_permlane32_swap_b32_e32 v80, v82
	v_mfma_f32_32x32x16_bf16 v[64:79], v[88:91], v[6:9], v[64:79]
	ds_read_b64_tr_b16 v[88:89], v14 offset:0x1200
	ds_read_b64_tr_b16 v[90:91], v14 offset:0x1a00
	v_permlane32_swap_b32_e32 v81, v83
	s_mov_b32 s49, s81
	v_ashrrev_i32_e32 v181, 31, v180
	s_xor_b64 s[82:83], s[96:97], -1
	v_mfma_f32_32x32x16_bf16 v[64:79], v[92:95], v[10:13], v[64:79]
	ds_read_b64_tr_b16 v[92:93], v14 offset:0x2200
	ds_read_b64_tr_b16 v[94:95], v14 offset:0x2a00
	s_mov_b64 s[96:97], 0
	v_mfma_f32_32x32x16_bf16 v[64:79], v[96:99], v[80:83], v[64:79]
	ds_read_b64_tr_b16 v[96:97], v14 offset:0x3200
	ds_read_b64_tr_b16 v[98:99], v14 offset:0x3a00
	s_nop 0
	s_waitcnt lgkmcnt(0)
	s_nop 0
	v_mfma_f32_32x32x16_bf16 v[48:63], v[84:87], v[2:5], v[48:63]
	ds_read_b64_tr_b16 v[84:85], v14 offset:0x400
	ds_read_b64_tr_b16 v[86:87], v14 offset:0xc00
	v_mfma_f32_32x32x16_bf16 v[48:63], v[88:91], v[6:9], v[48:63]
	ds_read_b64_tr_b16 v[88:89], v14 offset:0x1400
	ds_read_b64_tr_b16 v[90:91], v14 offset:0x1c00
	v_mfma_f32_32x32x16_bf16 v[48:63], v[92:95], v[10:13], v[48:63]
	ds_read_b64_tr_b16 v[92:93], v14 offset:0x2400
	ds_read_b64_tr_b16 v[94:95], v14 offset:0x2c00
	v_mfma_f32_32x32x16_bf16 v[48:63], v[96:99], v[80:83], v[48:63]
	ds_read_b64_tr_b16 v[96:97], v14 offset:0x3400
	ds_read_b64_tr_b16 v[98:99], v14 offset:0x3c00
	s_nop 0
	s_waitcnt lgkmcnt(0)
	s_nop 0
	v_mfma_f32_32x32x16_bf16 v[32:47], v[84:87], v[2:5], v[32:47]
	ds_read_b64_tr_b16 v[84:85], v14 offset:0x600
	ds_read_b64_tr_b16 v[86:87], v14 offset:0xe00
	v_mfma_f32_32x32x16_bf16 v[32:47], v[88:91], v[6:9], v[32:47]
	ds_read_b64_tr_b16 v[88:89], v14 offset:0x1600
	ds_read_b64_tr_b16 v[90:91], v14 offset:0x1e00
	v_mfma_f32_32x32x16_bf16 v[32:47], v[92:95], v[10:13], v[32:47]
	ds_read_b64_tr_b16 v[92:93], v14 offset:0x2600
	ds_read_b64_tr_b16 v[94:95], v14 offset:0x2e00
	v_mfma_f32_32x32x16_bf16 v[32:47], v[96:99], v[80:83], v[32:47]
	ds_read_b64_tr_b16 v[96:97], v14 offset:0x3600
	ds_read_b64_tr_b16 v[98:99], v14 offset:0x3e00
	s_nop 0
	s_waitcnt lgkmcnt(0)
	s_barrier
; __device__ __forceinline__ float bf_lo(unsigned w) { return __uint_as_float(w << 16); }
; __device__ __forceinline__ float bf_hi(unsigned w) { return __uint_as_float(w & 0xffff0000u); }
; __device__ __forceinline__ float siluf_(float v) { return v * sigmoidf_(v); }
; __device__ __forceinline__ void attn_block(const Params& p, LAS unsigned char* lds, int h, int qb) {
;     ...
;     const float il = __builtin_amdgcn_rcpf(l_reg);
;     const bf16_t* zp = proj + (size_t)qrow * NP + C_ZA + h * 128; unsigned char* ya8 = p.ws + O_YA8;
; #pragma unroll
;     for (int d0 = 0; d0 < 4; ++d0)
; #pragma unroll
;         for (int rq = 0; rq < 4; ++rq) { const int dv = d0 * 32 + 8 * rq + 4 * hi; const u32x2 zz = *(const u32x2*)(zp + dv);
;             const float y0 = o[d0][rq * 4 + 0] * il * siluf_(bf_lo(zz.x)), y1 = o[d0][rq * 4 + 1] * il * siluf_(bf_hi(zz.x));
;             const float y2 = o[d0][rq * 4 + 2] * il * siluf_(bf_lo(zz.y)), y3 = o[d0][rq * 4 + 3] * il * siluf_(bf_hi(zz.y));
;             int x8 = __builtin_amdgcn_cvt_pk_fp8_f32(y0 * 64.f, y1 * 64.f, 0, false); x8 = __builtin_amdgcn_cvt_pk_fp8_f32(y2 * 64.f, y3 * 64.f, x8, true);
;             *(int*)(ya8 + (size_t)qrow * 1024 + h * 128 + dv) = x8; }
	v_mfma_f32_32x32x16_bf16 v[16:31], v[84:87], v[2:5], v[16:31]
	v_mov_b64_e32 v[2:3], s[14:15]
	v_mad_i64_i32 v[2:3], s[0:1], v180, s31, v[2:3]
	v_lshl_add_u64 v[2:3], v[2:3], 0, s[48:49]
	s_mov_b64 s[0:1], 0xe200880
	v_lshlrev_b64 v[4:5], 10, v[180:181]
	v_lshl_add_u64 v[4:5], s[64:65], 0, v[4:5]
	v_mfma_f32_32x32x16_bf16 v[16:31], v[88:91], v[6:9], v[16:31]
	v_lshlrev_b32_e32 v6, 3, v193
	v_mov_b32_e32 v7, v1
	v_lshl_add_u64 v[6:7], v[2:3], 0, v[6:7]
	v_lshl_add_u64 v[2:3], v[6:7], 0, s[0:1]
	global_load_dwordx2 v[128:129], v[2:3], off offset:0
	global_load_dwordx2 v[130:131], v[2:3], off offset:16
	global_load_dwordx2 v[132:133], v[2:3], off offset:32
	global_load_dwordx2 v[134:135], v[2:3], off offset:48
	global_load_dwordx2 v[136:137], v[2:3], off offset:64
	global_load_dwordx2 v[138:139], v[2:3], off offset:80
	global_load_dwordx2 v[140:141], v[2:3], off offset:96
	global_load_dwordx2 v[142:143], v[2:3], off offset:112
	global_load_dwordx2 v[144:145], v[2:3], off offset:128
	global_load_dwordx2 v[146:147], v[2:3], off offset:144
	global_load_dwordx2 v[148:149], v[2:3], off offset:160
	global_load_dwordx2 v[150:151], v[2:3], off offset:176
	global_load_dwordx2 v[152:153], v[2:3], off offset:192
	global_load_dwordx2 v[154:155], v[2:3], off offset:208
	global_load_dwordx2 v[156:157], v[2:3], off offset:224
	global_load_dwordx2 v[158:159], v[2:3], off offset:240
	s_mov_b32 s0, 0xe200000
	v_add_co_u32_e32 v6, vcc, s0, v6
	v_mfma_f32_32x32x16_bf16 v[16:31], v[92:95], v[10:13], v[16:31]
	s_nop 0
	v_addc_co_u32_e32 v7, vcc, 0, v7, vcc
	v_rcp_f32_e32 v8, v0
	v_lshlrev_b32_e32 v0, 2, v193
	v_lshl_add_u64 v[4:5], v[4:5], 0, v[0:1]
	s_and_b64 vcc, exec, s[82:83]
	v_mul_f32_e32 v9, v8, v64
	v_mul_f32_e32 v0, v8, v68
	v_mfma_f32_32x32x16_bf16 v[16:31], v[96:99], v[80:83], v[16:31]
	s_waitcnt vmcnt(15)
	v_mov_b32_e32 v6, v128
	v_mov_b32_e32 v7, v129
	v_lshlrev_b32_e32 v10, 16, v6
	v_mul_f32_e32 v11, 0xbfb8aa3b, v10
	v_exp_f32_e32 v11, v11
	v_and_b32_e32 v6, 0xffff0000, v6
	v_add_f32_e32 v11, 1.0, v11
	v_rcp_f32_e32 v11, v11
	s_nop 0
	v_mul_f32_e32 v10, v11, v10
	v_mul_f32_e32 v11, 0xbfb8aa3b, v6
	v_exp_f32_e32 v11, v11
	v_mul_f32_e32 v9, v9, v10
	v_mul_f32_e32 v10, v8, v65
	v_mul_f32_e32 v9, 0x42800000, v9
	v_add_f32_e32 v11, 1.0, v11
	v_rcp_f32_e32 v11, v11
	s_nop 0
	v_mul_f32_e32 v6, v11, v6
	v_lshlrev_b32_e32 v11, 16, v7
	v_mul_f32_e32 v12, 0xbfb8aa3b, v11
	v_exp_f32_e32 v12, v12
	v_and_b32_e32 v7, 0xffff0000, v7
	v_mul_f32_e32 v6, v10, v6
	v_mul_f32_e32 v10, v8, v66
	v_add_f32_e32 v12, 1.0, v12
	v_rcp_f32_e32 v12, v12
	v_mul_f32_e32 v6, 0x42800000, v6
	v_mul_f32_e32 v11, v12, v11
	v_mul_f32_e32 v12, 0xbfb8aa3b, v7
	v_exp_f32_e32 v12, v12
	v_mul_f32_e32 v10, v10, v11
	v_mul_f32_e32 v11, v8, v67
	v_add_f32_e32 v12, 1.0, v12
	v_rcp_f32_e32 v12, v12
	s_nop 0
	v_mul_f32_e32 v7, v12, v7
	v_mul_f32_e32 v7, v11, v7
	v_mov_b32_e32 v11, v1
	v_cvt_pk_fp8_f32 v11, v9, v6
	v_mul_f32_e32 v6, 0x42800000, v10
	v_mul_f32_e32 v7, 0x42800000, v7
	v_cvt_pk_fp8_f32 v11, v6, v7 op_sel:[0,0,1]
	global_store_dword v[4:5], v11, off
	s_waitcnt vmcnt(15)
	v_mov_b32_e32 v6, v130
	v_mov_b32_e32 v7, v131
	v_lshlrev_b32_e32 v9, 16, v6
	v_mul_f32_e32 v10, 0xbfb8aa3b, v9
	v_exp_f32_e32 v10, v10
	v_and_b32_e32 v6, 0xffff0000, v6
	v_add_f32_e32 v10, 1.0, v10
	v_rcp_f32_e32 v10, v10
	s_nop 0
	v_mul_f32_e32 v9, v10, v9
	v_mul_f32_e32 v10, 0xbfb8aa3b, v6
	v_exp_f32_e32 v10, v10
	v_mul_f32_e32 v0, v0, v9
	v_mul_f32_e32 v9, v8, v69
	v_mul_f32_e32 v0, 0x42800000, v0
	v_add_f32_e32 v10, 1.0, v10
	v_rcp_f32_e32 v10, v10
	s_nop 0
	v_mul_f32_e32 v6, v10, v6
	v_lshlrev_b32_e32 v10, 16, v7
	v_mul_f32_e32 v11, 0xbfb8aa3b, v10
	v_exp_f32_e32 v11, v11
	v_and_b32_e32 v7, 0xffff0000, v7
	v_mul_f32_e32 v6, v9, v6
	v_mul_f32_e32 v9, v8, v70
	v_add_f32_e32 v11, 1.0, v11
	v_rcp_f32_e32 v11, v11
	v_mul_f32_e32 v6, 0x42800000, v6
	v_mul_f32_e32 v10, v11, v10
	v_mul_f32_e32 v11, 0xbfb8aa3b, v7
	v_exp_f32_e32 v11, v11
	v_mul_f32_e32 v9, v9, v10
	v_mul_f32_e32 v10, v8, v71
	v_add_f32_e32 v11, 1.0, v11
	v_rcp_f32_e32 v11, v11
	s_nop 0
	v_mul_f32_e32 v7, v11, v7
	v_mul_f32_e32 v7, v10, v7
	v_mov_b32_e32 v10, v1
	v_cvt_pk_fp8_f32 v10, v0, v6
	v_mul_f32_e32 v0, 0x42800000, v9
	v_mul_f32_e32 v6, 0x42800000, v7
	v_cvt_pk_fp8_f32 v10, v0, v6 op_sel:[0,0,1]
	v_mul_f32_e32 v0, v8, v72
	global_store_dword v[4:5], v10, off offset:8
	s_waitcnt vmcnt(15)
	v_mov_b32_e32 v6, v132
	v_mov_b32_e32 v7, v133
	v_lshlrev_b32_e32 v9, 16, v6
	v_mul_f32_e32 v10, 0xbfb8aa3b, v9
	v_exp_f32_e32 v10, v10
	v_and_b32_e32 v6, 0xffff0000, v6
	v_add_f32_e32 v10, 1.0, v10
	v_rcp_f32_e32 v10, v10
	s_nop 0
	v_mul_f32_e32 v9, v10, v9
	v_mul_f32_e32 v10, 0xbfb8aa3b, v6
	v_exp_f32_e32 v10, v10
	v_mul_f32_e32 v0, v0, v9
	v_mul_f32_e32 v9, v8, v73
	v_mul_f32_e32 v0, 0x42800000, v0
	v_add_f32_e32 v10, 1.0, v10
	v_rcp_f32_e32 v10, v10
	s_nop 0
	v_mul_f32_e32 v6, v10, v6
	v_lshlrev_b32_e32 v10, 16, v7
	v_mul_f32_e32 v11, 0xbfb8aa3b, v10
	v_exp_f32_e32 v11, v11
	v_and_b32_e32 v7, 0xffff0000, v7
	v_mul_f32_e32 v6, v9, v6
	v_mul_f32_e32 v9, v8, v74
	v_add_f32_e32 v11, 1.0, v11
	v_rcp_f32_e32 v11, v11
	v_mul_f32_e32 v6, 0x42800000, v6
	v_mul_f32_e32 v10, v11, v10
	v_mul_f32_e32 v11, 0xbfb8aa3b, v7
	v_exp_f32_e32 v11, v11
	v_mul_f32_e32 v9, v9, v10
	v_mul_f32_e32 v10, v8, v75
	v_add_f32_e32 v11, 1.0, v11
	v_rcp_f32_e32 v11, v11
	s_nop 0
	v_mul_f32_e32 v7, v11, v7
	v_mul_f32_e32 v7, v10, v7
	v_mov_b32_e32 v10, v1
	v_cvt_pk_fp8_f32 v10, v0, v6
	v_mul_f32_e32 v0, 0x42800000, v9
	v_mul_f32_e32 v6, 0x42800000, v7
	v_cvt_pk_fp8_f32 v10, v0, v6 op_sel:[0,0,1]
	v_mul_f32_e32 v0, v8, v76
	global_store_dword v[4:5], v10, off offset:16
	s_waitcnt vmcnt(15)
; __device__ __forceinline__ float bf_lo(unsigned w) { return __uint_as_float(w << 16); }
; __device__ __forceinline__ float bf_hi(unsigned w) { return __uint_as_float(w & 0xffff0000u); }
; __device__ __forceinline__ float siluf_(float v) { return v * sigmoidf_(v); }
; __device__ __forceinline__ void attn_block(const Params& p, LAS unsigned char* lds, int h, int qb) {
;     ...
;     const float il = __builtin_amdgcn_rcpf(l_reg);
;     const bf16_t* zp = proj + (size_t)qrow * NP + C_ZA + h * 128; unsigned char* ya8 = p.ws + O_YA8;
; #pragma unroll
;     for (int d0 = 0; d0 < 4; ++d0)
; #pragma unroll
;         for (int rq = 0; rq < 4; ++rq) { const int dv = d0 * 32 + 8 * rq + 4 * hi; const u32x2 zz = *(const u32x2*)(zp + dv);
;             const float y0 = o[d0][rq * 4 + 0] * il * siluf_(bf_lo(zz.x)), y1 = o[d0][rq * 4 + 1] * il * siluf_(bf_hi(zz.x));
;             const float y2 = o[d0][rq * 4 + 2] * il * siluf_(bf_lo(zz.y)), y3 = o[d0][rq * 4 + 3] * il * siluf_(bf_hi(zz.y));
;             int x8 = __builtin_amdgcn_cvt_pk_fp8_f32(y0 * 64.f, y1 * 64.f, 0, false); x8 = __builtin_amdgcn_cvt_pk_fp8_f32(y2 * 64.f, y3 * 64.f, x8, true);
;             *(int*)(ya8 + (size_t)qrow * 1024 + h * 128 + dv) = x8; }
	v_mov_b32_e32 v6, v134
	v_mov_b32_e32 v7, v135
	v_lshlrev_b32_e32 v9, 16, v6
	v_mul_f32_e32 v10, 0xbfb8aa3b, v9
	v_exp_f32_e32 v10, v10
	v_and_b32_e32 v6, 0xffff0000, v6
	v_add_f32_e32 v10, 1.0, v10
	v_rcp_f32_e32 v10, v10
	s_nop 0
	v_mul_f32_e32 v9, v10, v9
	v_mul_f32_e32 v10, 0xbfb8aa3b, v6
	v_exp_f32_e32 v10, v10
	v_mul_f32_e32 v0, v0, v9
	v_mul_f32_e32 v9, v8, v77
	v_mul_f32_e32 v0, 0x42800000, v0
	v_add_f32_e32 v10, 1.0, v10
	v_rcp_f32_e32 v10, v10
	s_nop 0
	v_mul_f32_e32 v6, v10, v6
	v_lshlrev_b32_e32 v10, 16, v7
	v_mul_f32_e32 v11, 0xbfb8aa3b, v10
	v_exp_f32_e32 v11, v11
	v_and_b32_e32 v7, 0xffff0000, v7
	v_mul_f32_e32 v6, v9, v6
	v_mul_f32_e32 v9, v8, v78
	v_add_f32_e32 v11, 1.0, v11
	v_rcp_f32_e32 v11, v11
	v_mul_f32_e32 v6, 0x42800000, v6
	v_mul_f32_e32 v10, v11, v10
	v_mul_f32_e32 v11, 0xbfb8aa3b, v7
	v_exp_f32_e32 v11, v11
	v_mul_f32_e32 v9, v9, v10
	v_mul_f32_e32 v10, v8, v79
	v_add_f32_e32 v11, 1.0, v11
	v_rcp_f32_e32 v11, v11
	s_nop 0
	v_mul_f32_e32 v7, v11, v7
	v_mul_f32_e32 v7, v10, v7
	v_mov_b32_e32 v10, v1
	v_cvt_pk_fp8_f32 v10, v0, v6
	v_mul_f32_e32 v0, 0x42800000, v9
	v_mul_f32_e32 v6, 0x42800000, v7
	v_cvt_pk_fp8_f32 v10, v0, v6 op_sel:[0,0,1]
	v_mul_f32_e32 v0, v8, v48
	global_store_dword v[4:5], v10, off offset:24
	s_waitcnt vmcnt(15)
	v_mov_b32_e32 v6, v136
	v_mov_b32_e32 v7, v137
	v_lshlrev_b32_e32 v9, 16, v6
	v_mul_f32_e32 v10, 0xbfb8aa3b, v9
	v_exp_f32_e32 v10, v10
	v_and_b32_e32 v6, 0xffff0000, v6
	v_add_f32_e32 v10, 1.0, v10
	v_rcp_f32_e32 v10, v10
	s_nop 0
	v_mul_f32_e32 v9, v10, v9
	v_mul_f32_e32 v10, 0xbfb8aa3b, v6
	v_exp_f32_e32 v10, v10
	v_mul_f32_e32 v0, v0, v9
	v_mul_f32_e32 v9, v8, v49
	v_mul_f32_e32 v0, 0x42800000, v0
	v_add_f32_e32 v10, 1.0, v10
	v_rcp_f32_e32 v10, v10
	s_nop 0
	v_mul_f32_e32 v6, v10, v6
	v_lshlrev_b32_e32 v10, 16, v7
	v_mul_f32_e32 v11, 0xbfb8aa3b, v10
	v_exp_f32_e32 v11, v11
	v_and_b32_e32 v7, 0xffff0000, v7
	v_mul_f32_e32 v6, v9, v6
	v_mul_f32_e32 v9, v8, v50
	v_add_f32_e32 v11, 1.0, v11
	v_rcp_f32_e32 v11, v11
	v_mul_f32_e32 v6, 0x42800000, v6
	v_mul_f32_e32 v10, v11, v10
	v_mul_f32_e32 v11, 0xbfb8aa3b, v7
	v_exp_f32_e32 v11, v11
	v_mul_f32_e32 v9, v9, v10
	v_mul_f32_e32 v10, v8, v51
	v_add_f32_e32 v11, 1.0, v11
	v_rcp_f32_e32 v11, v11
	s_nop 0
	v_mul_f32_e32 v7, v11, v7
	v_mul_f32_e32 v7, v10, v7
	v_mov_b32_e32 v10, v1
	v_cvt_pk_fp8_f32 v10, v0, v6
	v_mul_f32_e32 v0, 0x42800000, v9
	v_mul_f32_e32 v6, 0x42800000, v7
	v_cvt_pk_fp8_f32 v10, v0, v6 op_sel:[0,0,1]
	v_mul_f32_e32 v0, v8, v52
	global_store_dword v[4:5], v10, off offset:32
	s_waitcnt vmcnt(15)
	v_mov_b32_e32 v6, v138
	v_mov_b32_e32 v7, v139
	v_lshlrev_b32_e32 v9, 16, v6
	v_mul_f32_e32 v10, 0xbfb8aa3b, v9
	v_exp_f32_e32 v10, v10
	v_and_b32_e32 v6, 0xffff0000, v6
	v_add_f32_e32 v10, 1.0, v10
	v_rcp_f32_e32 v10, v10
	s_nop 0
	v_mul_f32_e32 v9, v10, v9
	v_mul_f32_e32 v10, 0xbfb8aa3b, v6
	v_exp_f32_e32 v10, v10
	v_mul_f32_e32 v0, v0, v9
	v_mul_f32_e32 v9, v8, v53
	v_mul_f32_e32 v0, 0x42800000, v0
	v_add_f32_e32 v10, 1.0, v10
	v_rcp_f32_e32 v10, v10
	s_nop 0
	v_mul_f32_e32 v6, v10, v6
	v_lshlrev_b32_e32 v10, 16, v7
	v_mul_f32_e32 v11, 0xbfb8aa3b, v10
	v_exp_f32_e32 v11, v11
	v_and_b32_e32 v7, 0xffff0000, v7
	v_mul_f32_e32 v6, v9, v6
	v_mul_f32_e32 v9, v8, v54
	v_add_f32_e32 v11, 1.0, v11
	v_rcp_f32_e32 v11, v11
	v_mul_f32_e32 v6, 0x42800000, v6
	v_mul_f32_e32 v10, v11, v10
	v_mul_f32_e32 v11, 0xbfb8aa3b, v7
	v_exp_f32_e32 v11, v11
	v_mul_f32_e32 v9, v9, v10
	v_mul_f32_e32 v10, v8, v55
	v_add_f32_e32 v11, 1.0, v11
	v_rcp_f32_e32 v11, v11
	s_nop 0
	v_mul_f32_e32 v7, v11, v7
	v_mul_f32_e32 v7, v10, v7
	v_mov_b32_e32 v10, v1
	v_cvt_pk_fp8_f32 v10, v0, v6
	v_mul_f32_e32 v0, 0x42800000, v9
	v_mul_f32_e32 v6, 0x42800000, v7
	v_cvt_pk_fp8_f32 v10, v0, v6 op_sel:[0,0,1]
	v_mul_f32_e32 v0, v8, v56
	global_store_dword v[4:5], v10, off offset:40
	s_waitcnt vmcnt(15)
	v_mov_b32_e32 v6, v140
	v_mov_b32_e32 v7, v141
	v_lshlrev_b32_e32 v9, 16, v6
	v_mul_f32_e32 v10, 0xbfb8aa3b, v9
	v_exp_f32_e32 v10, v10
	v_and_b32_e32 v6, 0xffff0000, v6
	v_add_f32_e32 v10, 1.0, v10
	v_rcp_f32_e32 v10, v10
	s_nop 0
	v_mul_f32_e32 v9, v10, v9
	v_mul_f32_e32 v10, 0xbfb8aa3b, v6
	v_exp_f32_e32 v10, v10
	v_mul_f32_e32 v0, v0, v9
	v_mul_f32_e32 v9, v8, v57
	v_mul_f32_e32 v0, 0x42800000, v0
	v_add_f32_e32 v10, 1.0, v10
	v_rcp_f32_e32 v10, v10
	s_nop 0
	v_mul_f32_e32 v6, v10, v6
	v_lshlrev_b32_e32 v10, 16, v7
	v_mul_f32_e32 v11, 0xbfb8aa3b, v10
	v_exp_f32_e32 v11, v11
	v_and_b32_e32 v7, 0xffff0000, v7
	v_mul_f32_e32 v6, v9, v6
	v_mul_f32_e32 v9, v8, v58
	v_add_f32_e32 v11, 1.0, v11
	v_rcp_f32_e32 v11, v11
	v_mul_f32_e32 v6, 0x42800000, v6
	v_mul_f32_e32 v10, v11, v10
	v_mul_f32_e32 v11, 0xbfb8aa3b, v7
	v_exp_f32_e32 v11, v11
	v_mul_f32_e32 v9, v9, v10
	v_mul_f32_e32 v10, v8, v59
	v_add_f32_e32 v11, 1.0, v11
	v_rcp_f32_e32 v11, v11
	s_nop 0
	v_mul_f32_e32 v7, v11, v7
	v_mul_f32_e32 v7, v10, v7
	v_mov_b32_e32 v10, v1
	v_cvt_pk_fp8_f32 v10, v0, v6
	v_mul_f32_e32 v0, 0x42800000, v9
	v_mul_f32_e32 v6, 0x42800000, v7
	v_cvt_pk_fp8_f32 v10, v0, v6 op_sel:[0,0,1]
	v_mul_f32_e32 v0, v8, v60
	global_store_dword v[4:5], v10, off offset:48
	s_waitcnt vmcnt(15)
; __device__ __forceinline__ float bf_lo(unsigned w) { return __uint_as_float(w << 16); }
; __device__ __forceinline__ float bf_hi(unsigned w) { return __uint_as_float(w & 0xffff0000u); }
; __device__ __forceinline__ float siluf_(float v) { return v * sigmoidf_(v); }
; __device__ __forceinline__ void attn_block(const Params& p, LAS unsigned char* lds, int h, int qb) {
;     ...
;     const float il = __builtin_amdgcn_rcpf(l_reg);
;     const bf16_t* zp = proj + (size_t)qrow * NP + C_ZA + h * 128; unsigned char* ya8 = p.ws + O_YA8;
; #pragma unroll
;     for (int d0 = 0; d0 < 4; ++d0)
; #pragma unroll
;         for (int rq = 0; rq < 4; ++rq) { const int dv = d0 * 32 + 8 * rq + 4 * hi; const u32x2 zz = *(const u32x2*)(zp + dv);
;             const float y0 = o[d0][rq * 4 + 0] * il * siluf_(bf_lo(zz.x)), y1 = o[d0][rq * 4 + 1] * il * siluf_(bf_hi(zz.x));
;             const float y2 = o[d0][rq * 4 + 2] * il * siluf_(bf_lo(zz.y)), y3 = o[d0][rq * 4 + 3] * il * siluf_(bf_hi(zz.y));
;             int x8 = __builtin_amdgcn_cvt_pk_fp8_f32(y0 * 64.f, y1 * 64.f, 0, false); x8 = __builtin_amdgcn_cvt_pk_fp8_f32(y2 * 64.f, y3 * 64.f, x8, true);
;             *(int*)(ya8 + (size_t)qrow * 1024 + h * 128 + dv) = x8; }
	v_mov_b32_e32 v6, v142
	v_mov_b32_e32 v7, v143
	v_lshlrev_b32_e32 v9, 16, v6
	v_mul_f32_e32 v10, 0xbfb8aa3b, v9
	v_exp_f32_e32 v10, v10
	v_and_b32_e32 v6, 0xffff0000, v6
	v_add_f32_e32 v10, 1.0, v10
	v_rcp_f32_e32 v10, v10
	s_nop 0
	v_mul_f32_e32 v9, v10, v9
	v_mul_f32_e32 v10, 0xbfb8aa3b, v6
	v_exp_f32_e32 v10, v10
	v_mul_f32_e32 v0, v0, v9
	v_mul_f32_e32 v9, v8, v61
	v_mul_f32_e32 v0, 0x42800000, v0
	v_add_f32_e32 v10, 1.0, v10
	v_rcp_f32_e32 v10, v10
	s_nop 0
	v_mul_f32_e32 v6, v10, v6
	v_lshlrev_b32_e32 v10, 16, v7
	v_mul_f32_e32 v11, 0xbfb8aa3b, v10
	v_exp_f32_e32 v11, v11
	v_and_b32_e32 v7, 0xffff0000, v7
	v_mul_f32_e32 v6, v9, v6
	v_mul_f32_e32 v9, v8, v62
	v_add_f32_e32 v11, 1.0, v11
	v_rcp_f32_e32 v11, v11
	v_mul_f32_e32 v6, 0x42800000, v6
	v_mul_f32_e32 v10, v11, v10
	v_mul_f32_e32 v11, 0xbfb8aa3b, v7
	v_exp_f32_e32 v11, v11
	v_mul_f32_e32 v9, v9, v10
	v_mul_f32_e32 v10, v8, v63
	v_add_f32_e32 v11, 1.0, v11
	v_rcp_f32_e32 v11, v11
	s_nop 0
	v_mul_f32_e32 v7, v11, v7
	v_mul_f32_e32 v7, v10, v7
	v_mov_b32_e32 v10, v1
	v_cvt_pk_fp8_f32 v10, v0, v6
	v_mul_f32_e32 v0, 0x42800000, v9
	v_mul_f32_e32 v6, 0x42800000, v7
	v_cvt_pk_fp8_f32 v10, v0, v6 op_sel:[0,0,1]
	v_mul_f32_e32 v0, v8, v32
	global_store_dword v[4:5], v10, off offset:56
	s_waitcnt vmcnt(15)
	v_mov_b32_e32 v6, v144
	v_mov_b32_e32 v7, v145
	v_lshlrev_b32_e32 v9, 16, v6
	v_mul_f32_e32 v10, 0xbfb8aa3b, v9
	v_exp_f32_e32 v10, v10
	v_and_b32_e32 v6, 0xffff0000, v6
	v_add_f32_e32 v10, 1.0, v10
	v_rcp_f32_e32 v10, v10
	s_nop 0
	v_mul_f32_e32 v9, v10, v9
	v_mul_f32_e32 v10, 0xbfb8aa3b, v6
	v_exp_f32_e32 v10, v10
	v_mul_f32_e32 v0, v0, v9
	v_mul_f32_e32 v9, v8, v33
	v_mul_f32_e32 v0, 0x42800000, v0
	v_add_f32_e32 v10, 1.0, v10
	v_rcp_f32_e32 v10, v10
	s_nop 0
	v_mul_f32_e32 v6, v10, v6
	v_lshlrev_b32_e32 v10, 16, v7
	v_mul_f32_e32 v11, 0xbfb8aa3b, v10
	v_exp_f32_e32 v11, v11
	v_and_b32_e32 v7, 0xffff0000, v7
	v_mul_f32_e32 v6, v9, v6
	v_mul_f32_e32 v9, v8, v34
	v_add_f32_e32 v11, 1.0, v11
	v_rcp_f32_e32 v11, v11
	v_mul_f32_e32 v6, 0x42800000, v6
	v_mul_f32_e32 v10, v11, v10
	v_mul_f32_e32 v11, 0xbfb8aa3b, v7
	v_exp_f32_e32 v11, v11
	v_mul_f32_e32 v9, v9, v10
	v_mul_f32_e32 v10, v8, v35
	v_add_f32_e32 v11, 1.0, v11
	v_rcp_f32_e32 v11, v11
	s_nop 0
	v_mul_f32_e32 v7, v11, v7
	v_mul_f32_e32 v7, v10, v7
	v_mov_b32_e32 v10, v1
	v_cvt_pk_fp8_f32 v10, v0, v6
	v_mul_f32_e32 v0, 0x42800000, v9
	v_mul_f32_e32 v6, 0x42800000, v7
	v_cvt_pk_fp8_f32 v10, v0, v6 op_sel:[0,0,1]
	v_mul_f32_e32 v0, v8, v36
	global_store_dword v[4:5], v10, off offset:64
	s_waitcnt vmcnt(15)
	v_mov_b32_e32 v6, v146
	v_mov_b32_e32 v7, v147
	v_lshlrev_b32_e32 v9, 16, v6
	v_mul_f32_e32 v10, 0xbfb8aa3b, v9
	v_exp_f32_e32 v10, v10
	v_and_b32_e32 v6, 0xffff0000, v6
	v_add_f32_e32 v10, 1.0, v10
	v_rcp_f32_e32 v10, v10
	s_nop 0
	v_mul_f32_e32 v9, v10, v9
	v_mul_f32_e32 v10, 0xbfb8aa3b, v6
	v_exp_f32_e32 v10, v10
	v_mul_f32_e32 v0, v0, v9
	v_mul_f32_e32 v9, v8, v37
	v_mul_f32_e32 v0, 0x42800000, v0
	v_add_f32_e32 v10, 1.0, v10
	v_rcp_f32_e32 v10, v10
	s_nop 0
	v_mul_f32_e32 v6, v10, v6
	v_lshlrev_b32_e32 v10, 16, v7
	v_mul_f32_e32 v11, 0xbfb8aa3b, v10
	v_exp_f32_e32 v11, v11
	v_and_b32_e32 v7, 0xffff0000, v7
	v_mul_f32_e32 v6, v9, v6
	v_mul_f32_e32 v9, v8, v38
	v_add_f32_e32 v11, 1.0, v11
	v_rcp_f32_e32 v11, v11
	v_mul_f32_e32 v6, 0x42800000, v6
	v_mul_f32_e32 v10, v11, v10
	v_mul_f32_e32 v11, 0xbfb8aa3b, v7
	v_exp_f32_e32 v11, v11
	v_mul_f32_e32 v9, v9, v10
	v_mul_f32_e32 v10, v8, v39
	v_add_f32_e32 v11, 1.0, v11
	v_rcp_f32_e32 v11, v11
	s_nop 0
	v_mul_f32_e32 v7, v11, v7
	v_mul_f32_e32 v7, v10, v7
	v_mov_b32_e32 v10, v1
	v_cvt_pk_fp8_f32 v10, v0, v6
	v_mul_f32_e32 v0, 0x42800000, v9
	v_mul_f32_e32 v6, 0x42800000, v7
	v_cvt_pk_fp8_f32 v10, v0, v6 op_sel:[0,0,1]
	v_mul_f32_e32 v0, v8, v40
	global_store_dword v[4:5], v10, off offset:72
	s_waitcnt vmcnt(15)
	v_mov_b32_e32 v6, v148
	v_mov_b32_e32 v7, v149
	v_lshlrev_b32_e32 v9, 16, v6
	v_mul_f32_e32 v10, 0xbfb8aa3b, v9
	v_exp_f32_e32 v10, v10
	v_and_b32_e32 v6, 0xffff0000, v6
	v_add_f32_e32 v10, 1.0, v10
	v_rcp_f32_e32 v10, v10
	s_nop 0
	v_mul_f32_e32 v9, v10, v9
	v_mul_f32_e32 v10, 0xbfb8aa3b, v6
	v_exp_f32_e32 v10, v10
	v_mul_f32_e32 v0, v0, v9
	v_mul_f32_e32 v9, v8, v41
	v_mul_f32_e32 v0, 0x42800000, v0
	v_add_f32_e32 v10, 1.0, v10
	v_rcp_f32_e32 v10, v10
	s_nop 0
	v_mul_f32_e32 v6, v10, v6
	v_lshlrev_b32_e32 v10, 16, v7
	v_mul_f32_e32 v11, 0xbfb8aa3b, v10
	v_exp_f32_e32 v11, v11
	v_and_b32_e32 v7, 0xffff0000, v7
	v_mul_f32_e32 v6, v9, v6
	v_mul_f32_e32 v9, v8, v42
	v_add_f32_e32 v11, 1.0, v11
	v_rcp_f32_e32 v11, v11
	v_mul_f32_e32 v6, 0x42800000, v6
	v_mul_f32_e32 v10, v11, v10
	v_mul_f32_e32 v11, 0xbfb8aa3b, v7
	v_exp_f32_e32 v11, v11
	v_mul_f32_e32 v9, v9, v10
	v_mul_f32_e32 v10, v8, v43
	v_add_f32_e32 v11, 1.0, v11
	v_rcp_f32_e32 v11, v11
	s_nop 0
	v_mul_f32_e32 v7, v11, v7
	v_mul_f32_e32 v7, v10, v7
	v_mov_b32_e32 v10, v1
	v_cvt_pk_fp8_f32 v10, v0, v6
	v_mul_f32_e32 v0, 0x42800000, v9
	v_mul_f32_e32 v6, 0x42800000, v7
	v_cvt_pk_fp8_f32 v10, v0, v6 op_sel:[0,0,1]
	v_mul_f32_e32 v0, v8, v44
	global_store_dword v[4:5], v10, off offset:80
	s_waitcnt vmcnt(15)
; __device__ __forceinline__ float bf_lo(unsigned w) { return __uint_as_float(w << 16); }
; __device__ __forceinline__ float bf_hi(unsigned w) { return __uint_as_float(w & 0xffff0000u); }
; __device__ __forceinline__ float siluf_(float v) { return v * sigmoidf_(v); }
; __device__ __forceinline__ void attn_block(const Params& p, LAS unsigned char* lds, int h, int qb) {
;     ...
;     const float il = __builtin_amdgcn_rcpf(l_reg);
;     const bf16_t* zp = proj + (size_t)qrow * NP + C_ZA + h * 128; unsigned char* ya8 = p.ws + O_YA8;
; #pragma unroll
;     for (int d0 = 0; d0 < 4; ++d0)
; #pragma unroll
;         for (int rq = 0; rq < 4; ++rq) { const int dv = d0 * 32 + 8 * rq + 4 * hi; const u32x2 zz = *(const u32x2*)(zp + dv);
;             const float y0 = o[d0][rq * 4 + 0] * il * siluf_(bf_lo(zz.x)), y1 = o[d0][rq * 4 + 1] * il * siluf_(bf_hi(zz.x));
;             const float y2 = o[d0][rq * 4 + 2] * il * siluf_(bf_lo(zz.y)), y3 = o[d0][rq * 4 + 3] * il * siluf_(bf_hi(zz.y));
;             int x8 = __builtin_amdgcn_cvt_pk_fp8_f32(y0 * 64.f, y1 * 64.f, 0, false); x8 = __builtin_amdgcn_cvt_pk_fp8_f32(y2 * 64.f, y3 * 64.f, x8, true);
;             *(int*)(ya8 + (size_t)qrow * 1024 + h * 128 + dv) = x8; }
	v_mov_b32_e32 v6, v150
	v_mov_b32_e32 v7, v151
	v_lshlrev_b32_e32 v9, 16, v6
	v_mul_f32_e32 v10, 0xbfb8aa3b, v9
	v_exp_f32_e32 v10, v10
	v_and_b32_e32 v6, 0xffff0000, v6
	v_add_f32_e32 v10, 1.0, v10
	v_rcp_f32_e32 v10, v10
	s_nop 0
	v_mul_f32_e32 v9, v10, v9
	v_mul_f32_e32 v10, 0xbfb8aa3b, v6
	v_exp_f32_e32 v10, v10
	v_mul_f32_e32 v0, v0, v9
	v_mul_f32_e32 v9, v8, v45
	v_mul_f32_e32 v0, 0x42800000, v0
	v_add_f32_e32 v10, 1.0, v10
	v_rcp_f32_e32 v10, v10
	s_nop 0
	v_mul_f32_e32 v6, v10, v6
	v_lshlrev_b32_e32 v10, 16, v7
	v_mul_f32_e32 v11, 0xbfb8aa3b, v10
	v_exp_f32_e32 v11, v11
	v_and_b32_e32 v7, 0xffff0000, v7
	v_mul_f32_e32 v6, v9, v6
	v_mul_f32_e32 v9, v8, v46
	v_add_f32_e32 v11, 1.0, v11
	v_rcp_f32_e32 v11, v11
	v_mul_f32_e32 v6, 0x42800000, v6
	v_mul_f32_e32 v10, v11, v10
	v_mul_f32_e32 v11, 0xbfb8aa3b, v7
	v_exp_f32_e32 v11, v11
	v_mul_f32_e32 v9, v9, v10
	v_mul_f32_e32 v10, v8, v47
	v_add_f32_e32 v11, 1.0, v11
	v_rcp_f32_e32 v11, v11
	s_nop 0
	v_mul_f32_e32 v7, v11, v7
	v_mul_f32_e32 v7, v10, v7
	v_mov_b32_e32 v10, v1
	v_cvt_pk_fp8_f32 v10, v0, v6
	v_mul_f32_e32 v0, 0x42800000, v9
	v_mul_f32_e32 v6, 0x42800000, v7
	v_cvt_pk_fp8_f32 v10, v0, v6 op_sel:[0,0,1]
	v_mul_f32_e32 v0, v8, v16
	global_store_dword v[4:5], v10, off offset:88
	s_waitcnt vmcnt(15)
	v_mov_b32_e32 v6, v152
	v_mov_b32_e32 v7, v153
	v_lshlrev_b32_e32 v9, 16, v6
	v_mul_f32_e32 v10, 0xbfb8aa3b, v9
	v_exp_f32_e32 v10, v10
	v_and_b32_e32 v6, 0xffff0000, v6
	v_add_f32_e32 v10, 1.0, v10
	v_rcp_f32_e32 v10, v10
	s_nop 0
	v_mul_f32_e32 v9, v10, v9
	v_mul_f32_e32 v10, 0xbfb8aa3b, v6
	v_exp_f32_e32 v10, v10
	v_mul_f32_e32 v0, v0, v9
	v_mul_f32_e32 v9, v8, v17
	v_mul_f32_e32 v0, 0x42800000, v0
	v_add_f32_e32 v10, 1.0, v10
	v_rcp_f32_e32 v10, v10
	s_nop 0
	v_mul_f32_e32 v6, v10, v6
	v_lshlrev_b32_e32 v10, 16, v7
	v_mul_f32_e32 v11, 0xbfb8aa3b, v10
	v_exp_f32_e32 v11, v11
	v_and_b32_e32 v7, 0xffff0000, v7
	v_mul_f32_e32 v6, v9, v6
	v_mul_f32_e32 v9, v8, v18
	v_add_f32_e32 v11, 1.0, v11
	v_rcp_f32_e32 v11, v11
	v_mul_f32_e32 v6, 0x42800000, v6
	v_mul_f32_e32 v10, v11, v10
	v_mul_f32_e32 v11, 0xbfb8aa3b, v7
	v_exp_f32_e32 v11, v11
	v_mul_f32_e32 v9, v9, v10
	v_mul_f32_e32 v10, v8, v19
	v_add_f32_e32 v11, 1.0, v11
	v_rcp_f32_e32 v11, v11
	s_nop 0
	v_mul_f32_e32 v7, v11, v7
	v_mul_f32_e32 v7, v10, v7
	v_mov_b32_e32 v10, v1
	v_cvt_pk_fp8_f32 v10, v0, v6
	v_mul_f32_e32 v0, 0x42800000, v9
	v_mul_f32_e32 v6, 0x42800000, v7
	v_cvt_pk_fp8_f32 v10, v0, v6 op_sel:[0,0,1]
	v_mul_f32_e32 v0, v8, v20
	global_store_dword v[4:5], v10, off offset:96
	s_waitcnt vmcnt(15)
	v_mov_b32_e32 v6, v154
	v_mov_b32_e32 v7, v155
	v_lshlrev_b32_e32 v9, 16, v6
	v_mul_f32_e32 v10, 0xbfb8aa3b, v9
	v_exp_f32_e32 v10, v10
	v_and_b32_e32 v6, 0xffff0000, v6
	v_add_f32_e32 v10, 1.0, v10
	v_rcp_f32_e32 v10, v10
	s_nop 0
	v_mul_f32_e32 v9, v10, v9
	v_mul_f32_e32 v10, 0xbfb8aa3b, v6
	v_exp_f32_e32 v10, v10
	v_mul_f32_e32 v0, v0, v9
	v_mul_f32_e32 v9, v8, v21
	v_mul_f32_e32 v0, 0x42800000, v0
	v_add_f32_e32 v10, 1.0, v10
	v_rcp_f32_e32 v10, v10
	s_nop 0
	v_mul_f32_e32 v6, v10, v6
	v_lshlrev_b32_e32 v10, 16, v7
	v_mul_f32_e32 v11, 0xbfb8aa3b, v10
	v_exp_f32_e32 v11, v11
	v_and_b32_e32 v7, 0xffff0000, v7
	v_mul_f32_e32 v6, v9, v6
	v_mul_f32_e32 v9, v8, v22
	v_add_f32_e32 v11, 1.0, v11
	v_rcp_f32_e32 v11, v11
	v_mul_f32_e32 v6, 0x42800000, v6
	v_mul_f32_e32 v10, v11, v10
	v_mul_f32_e32 v11, 0xbfb8aa3b, v7
	v_exp_f32_e32 v11, v11
	v_mul_f32_e32 v9, v9, v10
	v_mul_f32_e32 v10, v8, v23
	v_add_f32_e32 v11, 1.0, v11
	v_rcp_f32_e32 v11, v11
	s_nop 0
	v_mul_f32_e32 v7, v11, v7
	v_mul_f32_e32 v7, v10, v7
	v_mov_b32_e32 v10, v1
	v_cvt_pk_fp8_f32 v10, v0, v6
	v_mul_f32_e32 v0, 0x42800000, v9
	v_mul_f32_e32 v6, 0x42800000, v7
	v_cvt_pk_fp8_f32 v10, v0, v6 op_sel:[0,0,1]
	v_mul_f32_e32 v0, v8, v24
	global_store_dword v[4:5], v10, off offset:104
	s_waitcnt vmcnt(15)
	v_mov_b32_e32 v6, v156
	v_mov_b32_e32 v7, v157
	v_lshlrev_b32_e32 v9, 16, v6
	v_mul_f32_e32 v10, 0xbfb8aa3b, v9
	v_exp_f32_e32 v10, v10
	v_and_b32_e32 v6, 0xffff0000, v6
	v_add_f32_e32 v10, 1.0, v10
	v_rcp_f32_e32 v10, v10
	s_nop 0
	v_mul_f32_e32 v9, v10, v9
	v_mul_f32_e32 v10, 0xbfb8aa3b, v6
	v_exp_f32_e32 v10, v10
	v_mul_f32_e32 v0, v0, v9
	v_mul_f32_e32 v9, v8, v25
	v_mul_f32_e32 v0, 0x42800000, v0
	v_add_f32_e32 v10, 1.0, v10
	v_rcp_f32_e32 v10, v10
	s_nop 0
	v_mul_f32_e32 v6, v10, v6
	v_lshlrev_b32_e32 v10, 16, v7
	v_mul_f32_e32 v11, 0xbfb8aa3b, v10
	v_exp_f32_e32 v11, v11
	v_and_b32_e32 v7, 0xffff0000, v7
	v_mul_f32_e32 v6, v9, v6
	v_mul_f32_e32 v9, v8, v26
	v_add_f32_e32 v11, 1.0, v11
	v_rcp_f32_e32 v11, v11
	v_mul_f32_e32 v6, 0x42800000, v6
	v_mul_f32_e32 v10, v11, v10
	v_mul_f32_e32 v11, 0xbfb8aa3b, v7
	v_exp_f32_e32 v11, v11
	v_mul_f32_e32 v9, v9, v10
	v_mul_f32_e32 v10, v8, v27
	v_add_f32_e32 v11, 1.0, v11
	v_rcp_f32_e32 v11, v11
	s_nop 0
	v_mul_f32_e32 v7, v11, v7
	v_mul_f32_e32 v7, v10, v7
	v_mov_b32_e32 v10, v1
	v_cvt_pk_fp8_f32 v10, v0, v6
	v_mul_f32_e32 v0, 0x42800000, v9
	v_mul_f32_e32 v6, 0x42800000, v7
	v_cvt_pk_fp8_f32 v10, v0, v6 op_sel:[0,0,1]
	v_mul_f32_e32 v0, v8, v28
	global_store_dword v[4:5], v10, off offset:112
	s_waitcnt vmcnt(15)
	v_mov_b32_e32 v2, v158
	v_mov_b32_e32 v3, v159
	v_lshlrev_b32_e32 v6, 16, v2
	v_mul_f32_e32 v7, 0xbfb8aa3b, v6
	v_exp_f32_e32 v7, v7
	v_and_b32_e32 v2, 0xffff0000, v2
	v_add_f32_e32 v7, 1.0, v7
	v_rcp_f32_e32 v7, v7
	s_nop 0
	v_mul_f32_e32 v6, v7, v6
	v_mul_f32_e32 v7, 0xbfb8aa3b, v2
	v_exp_f32_e32 v7, v7
	v_mul_f32_e32 v0, v0, v6
	v_mul_f32_e32 v6, v8, v29
	v_mul_f32_e32 v0, 0x42800000, v0
	v_add_f32_e32 v7, 1.0, v7
	v_rcp_f32_e32 v7, v7
	s_nop 0
	v_mul_f32_e32 v2, v7, v2
	v_lshlrev_b32_e32 v7, 16, v3
	v_mul_f32_e32 v9, 0xbfb8aa3b, v7
	v_exp_f32_e32 v9, v9
	v_mul_f32_e32 v2, v6, v2
	v_mul_f32_e32 v6, v8, v30
	v_and_b32_e32 v3, 0xffff0000, v3
	v_add_f32_e32 v9, 1.0, v9
	v_rcp_f32_e32 v9, v9
	v_mul_f32_e32 v2, 0x42800000, v2
	v_mul_f32_e32 v7, v9, v7
	v_mul_f32_e32 v6, v6, v7
	v_mul_f32_e32 v7, v8, v31
	v_mul_f32_e32 v8, 0xbfb8aa3b, v3
	v_exp_f32_e32 v8, v8
	s_nop 0
	v_add_f32_e32 v8, 1.0, v8
	v_rcp_f32_e32 v8, v8
	s_nop 0
	v_mul_f32_e32 v3, v8, v3
	v_mul_f32_e32 v3, v7, v3
	v_mov_b32_e32 v7, v1
	v_cvt_pk_fp8_f32 v7, v0, v2
	v_mul_f32_e32 v0, 0x42800000, v6
	v_mul_f32_e32 v2, 0x42800000, v3
	v_cvt_pk_fp8_f32 v7, v0, v2 op_sel:[0,0,1]
	global_store_dword v[4:5], v7, off offset:120
	s_cbranch_vccnz .LBB0_320
; __device__ __forceinline__ int otid() { int t = threadIdx.x; asm volatile("" : "+v"(t)); return t; }
; __device__ __forceinline__ unsigned lds_addr(LAS unsigned char* p) { return (unsigned)(size_t)p; }
; __device__ __forceinline__ int v_rd_base(int lane) { return ((lane & 3) << 3) | (((lane >> 2) & 3) << 6) | (((lane >> 4) & 1) << 5) | (((lane >> 5) & 1) << 8); }
; __device__ __forceinline__ void attn_block(const Params& p, LAS unsigned char* lds, int h, int qb) {
;     const int tid = otid(), wid = __builtin_amdgcn_readfirstlane(tid >> 6), lane = tid & 63, r32 = lane & 31, hi = lane >> 5;
;     const bf16_t* qbuf = (const bf16_t*)(p.ws + O_Q); const bf16_t* Kh = (const bf16_t*)(p.ws + O_K) + h * 192; const bf16_t* Vh = (const bf16_t*)(p.ws + O_V) + h * 128;
;     bf16_t* proj = (bf16_t*)(p.ws + O_PROJ);
;     const int qrow = qb * 256 + wid * 32 + r32;
;     bf16x8 qr[12];
;     { const bf16_t* qp = qbuf + (size_t)qrow * QW + h * 192 + hi * 8;
; #pragma unroll
;       for (int d0 = 0; d0 < 12; ++d0) qr[d0] = *(const bf16x8*)(qp + d0 * 16); }
;     const int ntiles = qb * 4 + 4, my_last = qb * 4 + (wid >> 1);
;     int ksrc[3], vsrc[2];
; #pragma unroll
;     for (int i = 0; i < 3; ++i) { const int j = i * 512 + tid, row = j / 24, cp = j % 24, c = (cp & ~7) | ((cp & 7) ^ ((row >> 1) & 7)); ksrc[i] = (row * KW + c * 8) * 2; }
; #pragma unroll
;     for (int i = 0; i < 2; ++i) { const int off = (i * 512 + tid) * 16, sub = off >> 9, rem = (off & 511) >> 1, kk = (sub >> 2) * 8 + (rem >> 5), c = (sub & 3) * 32 + (rem & 31);
;         const int k = (kk & ~0xC) | ((kk & 4) << 1) | ((kk & 8) >> 1); vsrc[i] = (k * VW + c) * 2; }
;     const int vb0 = (int)lds_addr(lds) + v_rd_base(lane);
;     const unsigned ldsw = (unsigned)wid * 1024u;
;     ...
;     float m_reg = -1e30f, l_reg = 0.f; f32x16 o[4];
; #pragma unroll
;     for (int j = 0; j < 4; ++j) o[j] = (f32x16){};
;     f32x16 pA0, pA1, pB0, pB1; float mnA, mnB, alA = 1.f, alB = 1.f; bf16x8 pa0, pa1, pa2, pa3;
;     ...
;     ADMA(0, 0, 0); __syncthreads();
;     ADMA(1, 1, 1);
.LBB0_324:
	v_mov_b32_e32 v8, v199
	s_and_b64 s[0:1], s[96:97], exec
	s_cselect_b32 s34, s16, s53
	v_readfirstlane_b32 s35, v8
	s_ashr_i32 s17, s35, 6
	s_lshl_b32 s0, s34, 8
	s_lshl_b32 s1, s17, 5
	v_and_b32_e32 v47, 31, v8
	s_add_i32 s1, s1, s0
	v_bfe_u32 v193, v8, 5, 1
	v_or_b32_e32 v180, s1, v47
	v_mov_b64_e32 v[2:3], s[44:45]
	v_mad_i64_i32 v[2:3], s[0:1], v180, s60, v[2:3]
	v_lshlrev_b32_e32 v0, 4, v193
	v_lshl_add_u64 v[2:3], v[2:3], 0, v[0:1]
	global_load_dwordx4 v[128:131], v[2:3], off
	global_load_dwordx4 v[132:135], v[2:3], off offset:32
	global_load_dwordx4 v[136:139], v[2:3], off offset:64
	global_load_dwordx4 v[140:143], v[2:3], off offset:96
	global_load_dwordx4 v[144:147], v[2:3], off offset:128
	global_load_dwordx4 v[148:151], v[2:3], off offset:160
	global_load_dwordx4 v[152:155], v[2:3], off offset:192
	global_load_dwordx4 v[156:159], v[2:3], off offset:224
	global_load_dwordx4 v[160:163], v[2:3], off offset:256
	global_load_dwordx4 v[164:167], v[2:3], off offset:288
	global_load_dwordx4 v[168:171], v[2:3], off offset:320
	global_load_dwordx4 v[172:175], v[2:3], off offset:352
	s_mov_b32 s0, 0x2aaaaaab
	v_mul_hi_i32 v0, v8, s0
	v_lshrrev_b32_e32 v2, 31, v0
	v_ashrrev_i32_e32 v0, 2, v0
	v_add_u32_e32 v0, v0, v2
	v_mul_lo_u32 v2, v0, 24
	v_sub_u32_e32 v2, v8, v2
	v_lshrrev_b32_e32 v3, 1, v0
	v_bitop3_b32 v2, v3, v2, 7 bitop3:0x6c
	v_mul_lo_u32 v0, v0, s60
	v_lshl_add_u32 v34, v2, 4, v0
	v_add_u32_e32 v0, 0x200, v8
	v_mul_hi_i32 v2, v0, s0
	v_lshrrev_b32_e32 v3, 31, v2
	v_ashrrev_i32_e32 v2, 2, v2
	v_add_u32_e32 v2, v2, v3
	v_mul_lo_u32 v3, v2, 24
	v_sub_u32_e32 v0, v0, v3
	v_lshrrev_b32_e32 v3, 1, v2
	v_bitop3_b32 v0, v3, v0, 7 bitop3:0x6c
	v_mul_lo_u32 v2, v2, s60
	v_lshl_add_u32 v36, v0, 4, v2
	v_add_u32_e32 v0, 0x400, v8
	v_mul_hi_i32 v2, v0, s0
	v_lshrrev_b32_e32 v3, 31, v2
	v_ashrrev_i32_e32 v2, 2, v2
	v_add_u32_e32 v2, v2, v3
	v_mul_lo_u32 v3, v2, 24
	v_sub_u32_e32 v0, v0, v3
	v_lshrrev_b32_e32 v3, 1, v2
	v_bitop3_b32 v0, v3, v0, 7 bitop3:0x6c
	v_lshlrev_b32_e32 v3, 4, v8
	v_mul_lo_u32 v2, v2, s60
	v_add_u32_e32 v10, 0x2000, v3
	v_lshl_add_u32 v38, v0, 4, v2
	v_lshrrev_b32_e32 v9, 1, v8
	v_bfe_i32 v2, v8, 4, 24
	v_ashrrev_i32_e32 v10, 8, v10
	v_and_b32_e32 v5, 63, v8
	v_bfe_u32 v0, v8, 2, 2
	v_and_b32_e32 v40, 8, v9
	v_lshlrev_b32_e32 v6, 1, v8
	v_and_b32_e32 v44, 0x1ffff0, v2
	v_lshrrev_b32_e32 v2, 1, v2
	v_and_b32_e32 v43, 0x1ffff0, v10
	v_lshrrev_b32_e32 v10, 1, v10
	v_or_b32_e32 v4, v40, v0
	v_and_b32_e32 v41, 0xc0, v6
	v_and_b32_e32 v42, 48, v3
	v_and_b32_e32 v46, 4, v2
	v_and_b32_e32 v45, 4, v10
	v_lshlrev_b32_e32 v5, 3, v5
	v_and_b32_e32 v3, 0xc0, v3
	s_lshl_b32 s0, s17, 10
	s_add_i32 s80, 0, 0x10000
	v_or_b32_e32 v7, v42, v41
	v_or3_b32 v2, v44, v46, v4
	v_or3_b32 v4, v43, v45, v4
	v_and_or_b32 v3, v5, 24, v3
	v_and_b32_e32 v6, 32, v6
	v_and_b32_e32 v5, 0x100, v5
	s_add_i32 s1, s80, s0
	v_ashrrev_i32_e32 v35, 31, v34
	v_lshl_or_b32 v2, v2, 11, v7
	v_lshl_or_b32 v4, v4, 11, v7
	v_or3_b32 v218, v3, v6, v5
	v_lshl_add_u64 v[6:7], s[42:43], 0, v[34:35]
	s_mov_b32 m0, s1
	v_ashrrev_i32_e32 v37, 31, v36
	global_load_lds_dwordx4 v[6:7], off
	v_lshl_add_u64 v[6:7], s[42:43], 0, v[36:37]
	s_add_i32 m0, s1, 0x2000
	v_ashrrev_i32_e32 v39, 31, v38
	global_load_lds_dwordx4 v[6:7], off
	v_lshl_add_u64 v[6:7], s[42:43], 0, v[38:39]
	s_add_i32 m0, s1, 0x4000
	s_add_i32 s17, s0, 0
	v_ashrrev_i32_e32 v3, 31, v2
	global_load_lds_dwordx4 v[6:7], off
	v_lshl_add_u64 v[6:7], s[12:13], 0, v[2:3]
	s_mov_b32 m0, s17
	v_ashrrev_i32_e32 v5, 31, v4
	global_load_lds_dwordx4 v[6:7], off
	v_lshl_add_u64 v[6:7], s[12:13], 0, v[4:5]
	s_add_i32 m0, s17, 0x2000
	s_add_i32 s49, s17, 0x16000
	global_load_lds_dwordx4 v[6:7], off
	v_lshl_add_u64 v[6:7], s[66:67], 0, v[34:35]
	s_mov_b32 m0, s49
	s_add_i32 s0, s17, 0x18000
	s_waitcnt vmcnt(0) lgkmcnt(0)
	s_barrier
	global_load_lds_dwordx4 v[6:7], off
	v_lshl_add_u64 v[6:7], s[66:67], 0, v[36:37]
	s_mov_b32 m0, s0
	s_add_i32 s1, s17, 0x1a000
	global_load_lds_dwordx4 v[6:7], off
	v_lshl_add_u64 v[6:7], s[66:67], 0, v[38:39]
	s_mov_b32 m0, s1
	v_lshl_add_u64 v[2:3], s[68:69], 0, v[2:3]
	global_load_lds_dwordx4 v[6:7], off
	s_add_i32 m0, s17, 0x4000
	s_nop 0
	global_load_lds_dwordx4 v[2:3], off
	v_lshl_add_u64 v[2:3], s[68:69], 0, v[4:5]
	s_add_i32 m0, s17, 0x6000
	v_bitop3_b32 v4, v193, v9, 7 bitop3:0x78
	global_load_lds_dwordx4 v[2:3], off
	v_bfe_u32 v3, v8, 1, 3
	v_lshlrev_b32_e32 v48, 4, v4
	v_bitop3_b32 v4, v193, v3, 2 bitop3:0x36
	v_mov_b32_e32 v2, s80
	s_movk_i32 s80, 0x180
	v_lshlrev_b32_e32 v49, 4, v4
	v_bitop3_b32 v4, v193, v3, 4 bitop3:0x36
	v_bitop3_b32 v3, v193, v3, 6 bitop3:0x36
	v_mad_u32_u24 v2, v47, s80, v2
	v_lshlrev_b32_e32 v50, 4, v4
	v_lshlrev_b32_e32 v51, 4, v3
	v_add_u32_e32 v181, v48, v2
	v_add_u32_e32 v219, v49, v2
	v_add_u32_e32 v220, v50, v2
	v_add_u32_e32 v221, v51, v2
	ds_read_b128 v[2:5], v181 offset:0
	ds_read_b128 v[6:9], v181 offset:0x3000
	ds_read_b128 v[52:55], v219 offset:0
	ds_read_b128 v[56:59], v219 offset:0x3000
	s_cmp_lt_i32 s34, 0
	s_waitcnt lgkmcnt(0)
	s_nop 0
	v_mfma_f32_32x32x16_bf16 v[18:33], v[2:5], v[128:131], 0
	v_mfma_f32_32x32x16_bf16 v[2:17], v[6:9], v[128:131], 0
	v_mfma_f32_32x32x16_bf16 v[18:33], v[52:55], v[132:135], v[18:33]
	ds_read_b128 v[52:55], v220 offset:0
	v_mfma_f32_32x32x16_bf16 v[2:17], v[56:59], v[132:135], v[2:17]
	ds_read_b128 v[56:59], v220 offset:0x3000
	ds_read_b128 v[60:63], v221 offset:0
	ds_read_b128 v[64:67], v221 offset:0x3000
	s_nop 0
	s_waitcnt lgkmcnt(0)
; #define LAS __attribute__((address_space(3)))
; __device__ __forceinline__ unsigned lds_addr(LAS unsigned char* p) { return (unsigned)(size_t)p; }
; #define KGRP(B_, g_) do { KRD(B_[0], kb[(2 * (g_)) & 3], ((2 * (g_)) >> 2) * 128); KRD(B_[1], kb[(2 * (g_)) & 3], ((2 * (g_)) >> 2) * 128 + 12288); \
;                           KRD(B_[2], kb[(2 * (g_) + 1) & 3], ((2 * (g_) + 1) >> 2) * 128); KRD(B_[3], kb[(2 * (g_) + 1) & 3], ((2 * (g_) + 1) >> 2) * 128 + 12288); } while (0)
; #define KWAIT(B_, n_) asm volatile("s_waitcnt lgkmcnt(" #n_ ")" : "+v"(B_[0]), "+v"(B_[1]), "+v"(B_[2]), "+v"(B_[3]) :: "memory")
; #define KWAIT(B_, n_) asm volatile("s_waitcnt lgkmcnt(" #n_ ")" : "+v"(B_[0]), "+v"(B_[1]) :: "memory")
; __device__ __forceinline__ void partialSM(f32x16& p0, f32x16& p1, float& m_reg, float& mn, float& alpha) {
;     float pmax = p0[0];
; #pragma unroll
;     for (int r = 1; r < 16; ++r) pmax = fmaxf(pmax, p0[r]);
; #pragma unroll
;     for (int r = 0; r < 16; ++r) pmax = fmaxf(pmax, p1[r]);
;     { auto rr = __builtin_amdgcn_permlane32_swap(__float_as_uint(pmax), __float_as_uint(pmax), false, false);
;       pmax = fmaxf(__uint_as_float(rr[0]), __uint_as_float(rr[1])); }
;     constexpr float C2 = 1.4426950408889634f * SCALE;
;     if (__builtin_expect(__all((pmax - m_reg) * SCALE <= THR), 1)) { mn = m_reg; alpha = 1.f; }
;     else { mn = fmaxf(m_reg, pmax); alpha = __builtin_amdgcn_exp2f((m_reg - mn) * C2); m_reg = mn; }
;     const float mnL = -mn * C2;
; #pragma unroll
;     for (int r = 0; r < 16; ++r) p0[r] = fmaf(p0[r], C2, mnL);
; #pragma unroll
;     for (int r = 0; r < 16; ++r) p1[r] = fmaf(p1[r], C2, mnL);
; #pragma unroll
;     for (int r = 0; r < 16; ++r) p0[r] = __builtin_amdgcn_exp2f(p0[r]);
; }
; __device__ __forceinline__ void qkt(int kboff, f32x16& p0, f32x16& p1, LAS unsigned char* lds, int r32, int hi, const bf16x8* qr) {
;     p0 = (f32x16){}; p1 = (f32x16){};
;     unsigned kb[4];
; #pragma unroll
;     for (int dd = 0; dd < 4; ++dd) kb[dd] = lds_addr(lds) + K_OFF + kboff + r32 * 384 + (((2 * dd + hi) ^ ((r32 >> 1) & 7)) << 4);
;     ...
;     bf16x8 bA[4];
;     KGRP(bA, 0); KWAIT(bA, 0); KMMA(bA, 0);
;     KGRP(bA, 1); KWAIT(bA, 0); KMMA(bA, 1);
;     KGRP(bA, 2); KWAIT(bA, 0); KMMA(bA, 2);
;     KGRP(bA, 3); KWAIT(bA, 0); KMMA(bA, 3);
;     KGRP(bA, 4); KWAIT(bA, 0); KMMA(bA, 4);
;     KGRP(bA, 5); KWAIT(bA, 0); KMMA(bA, 5);
	s_nop 0
	v_mfma_f32_32x32x16_bf16 v[18:33], v[52:55], v[136:139], v[18:33]
	ds_read_b128 v[52:55], v181 offset:0x80
	v_mfma_f32_32x32x16_bf16 v[2:17], v[56:59], v[136:139], v[2:17]
	ds_read_b128 v[56:59], v181 offset:0x3080
	v_mfma_f32_32x32x16_bf16 v[18:33], v[60:63], v[140:143], v[18:33]
	ds_read_b128 v[60:63], v219 offset:0x80
	v_mfma_f32_32x32x16_bf16 v[2:17], v[64:67], v[140:143], v[2:17]
	ds_read_b128 v[64:67], v219 offset:0x3080
	s_nop 0
	s_waitcnt lgkmcnt(0)
	s_nop 0
	v_mfma_f32_32x32x16_bf16 v[18:33], v[52:55], v[144:147], v[18:33]
	ds_read_b128 v[52:55], v220 offset:0x80
	v_mfma_f32_32x32x16_bf16 v[2:17], v[56:59], v[144:147], v[2:17]
	ds_read_b128 v[56:59], v220 offset:0x3080
	v_mfma_f32_32x32x16_bf16 v[18:33], v[60:63], v[148:151], v[18:33]
	ds_read_b128 v[60:63], v221 offset:0x80
	v_mfma_f32_32x32x16_bf16 v[2:17], v[64:67], v[148:151], v[2:17]
	ds_read_b128 v[64:67], v221 offset:0x3080
	s_nop 0
	s_waitcnt lgkmcnt(0)
	s_nop 0
	v_mfma_f32_32x32x16_bf16 v[18:33], v[52:55], v[152:155], v[18:33]
	ds_read_b128 v[52:55], v181 offset:0x100
	v_mfma_f32_32x32x16_bf16 v[2:17], v[56:59], v[152:155], v[2:17]
	ds_read_b128 v[56:59], v181 offset:0x3100
	v_mfma_f32_32x32x16_bf16 v[18:33], v[60:63], v[156:159], v[18:33]
	ds_read_b128 v[60:63], v219 offset:0x100
	v_mfma_f32_32x32x16_bf16 v[2:17], v[64:67], v[156:159], v[2:17]
	ds_read_b128 v[64:67], v219 offset:0x3100
	s_nop 0
	s_waitcnt lgkmcnt(0)
	s_nop 0
	v_mfma_f32_32x32x16_bf16 v[18:33], v[52:55], v[160:163], v[18:33]
	ds_read_b128 v[52:55], v220 offset:0x100
	v_mfma_f32_32x32x16_bf16 v[2:17], v[56:59], v[160:163], v[2:17]
	ds_read_b128 v[56:59], v220 offset:0x3100
	v_mfma_f32_32x32x16_bf16 v[18:33], v[60:63], v[164:167], v[18:33]
	ds_read_b128 v[60:63], v221 offset:0x100
	v_mfma_f32_32x32x16_bf16 v[2:17], v[64:67], v[164:167], v[2:17]
	ds_read_b128 v[64:67], v221 offset:0x3100
	s_nop 0
	s_waitcnt lgkmcnt(0)
	s_waitcnt vmcnt(0) lgkmcnt(0)
	s_barrier
	v_mfma_f32_32x32x16_bf16 v[18:33], v[52:55], v[168:171], v[18:33]
	v_mfma_f32_32x32x16_bf16 v[18:33], v[60:63], v[172:175], v[18:33]
	v_mfma_f32_32x32x16_bf16 v[2:17], v[56:59], v[168:171], v[2:17]
	s_nop 10
	v_max_f32_e32 v52, v19, v19
	v_max_f32_e32 v53, v18, v18
	v_max_f32_e32 v52, v53, v52
	v_max3_f32 v52, v52, v20, v21
	v_max3_f32 v52, v52, v22, v23
	v_max3_f32 v52, v52, v24, v25
	v_max3_f32 v52, v52, v26, v27
	v_mfma_f32_32x32x16_bf16 v[2:17], v[64:67], v[172:175], v[2:17]
	v_max3_f32 v52, v52, v28, v29
	v_max3_f32 v52, v52, v30, v31
	v_max3_f32 v52, v52, v32, v33
	s_nop 8
	v_max3_f32 v52, v52, v2, v3
	v_max3_f32 v52, v52, v4, v5
	v_max3_f32 v52, v52, v6, v7
	v_max3_f32 v52, v52, v8, v9
	v_max3_f32 v52, v52, v10, v11
	v_max3_f32 v52, v52, v12, v13
	v_max3_f32 v52, v52, v14, v15
	v_max3_f32 v52, v52, v16, v17
	v_mov_b32_e32 v53, v52
	s_nop 1
	v_permlane32_swap_b32_e32 v52, v53
	v_max_f32_e32 v53, v53, v53
	v_max_f32_e32 v52, v52, v52
	v_max_f32_e32 v52, v52, v53
	v_add_f32_e32 v53, 0x7149f2ca, v52
	v_mul_f32_e32 v53, 0x3d93cd3a, v53
	v_cmp_ge_f32_e32 vcc, s63, v53
	s_cbranch_scc1 .LBB0_339
	s_lshl_b32 s34, s34, 2
	s_ashr_i32 s84, s35, 7
	s_add_i32 s80, s34, 4
	s_add_i32 s84, s84, s34
	s_cmp_eq_u64 vcc, exec
	v_max_f32_e32 v52, v52, v52
	v_max_f32_e32 v53, 0xf149f2ca, v52
	s_cselect_b64 vcc, -1, 0
	v_mov_b32_e32 v52, 0xf149f2ca
	v_cndmask_b32_e32 v244, v53, v52, vcc
	v_mul_f32_e32 v52, 0xbdd53b94, v244
	v_pk_fma_f32 v[214:215], v[2:3], s[52:53], v[52:53] op_sel_hi:[1,0,0]
	v_sub_f32_e32 v2, 0xf149f2ca, v53
	v_mul_f32_e32 v2, 0x3dd53b94, v2
	v_exp_f32_e32 v2, v2
	v_fmamk_f32 v18, v18, 0x3dd53b94, v52
	v_exp_f32_e32 v80, v18
	v_fmamk_f32 v18, v19, 0x3dd53b94, v52
	v_exp_f32_e32 v81, v18
	v_fmamk_f32 v18, v20, 0x3dd53b94, v52
	v_exp_f32_e32 v82, v18
	v_fmamk_f32 v18, v21, 0x3dd53b94, v52
	v_cndmask_b32_e64 v192, v2, 1.0, vcc
	v_add_u32_e32 v2, v44, v40
	v_exp_f32_e32 v83, v18
	v_fmamk_f32 v18, v22, 0x3dd53b94, v52
	v_add3_u32 v2, v2, v46, v0
	v_mul_u32_u24_e32 v47, 0x180, v47
	v_exp_f32_e32 v84, v18
	v_fmamk_f32 v18, v23, 0x3dd53b94, v52
	s_add_i32 s34, 0, 0x16000
	v_lshl_or_b32 v2, v2, 11, v41
	v_exp_f32_e32 v85, v18
	v_fmamk_f32 v18, v24, 0x3dd53b94, v52
	v_add_u32_e32 v3, s34, v47
	v_add_u32_e32 v2, v2, v42
	v_exp_f32_e32 v86, v18
	v_fmamk_f32 v18, v25, 0x3dd53b94, v52
	v_add_u32_e32 v226, v48, v3
	v_add_u32_e32 v227, v49, v3
	v_add_u32_e32 v228, v50, v3
	v_add_u32_e32 v229, v51, v3
	v_ashrrev_i32_e32 v3, 31, v2
	v_exp_f32_e32 v87, v18
	v_fmamk_f32 v18, v26, 0x3dd53b94, v52
	v_lshl_add_u64 v[182:183], s[50:51], 0, v[2:3]
	v_add_u32_e32 v2, v43, v40
	v_exp_f32_e32 v88, v18
	v_fmamk_f32 v18, v27, 0x3dd53b94, v52
	v_add3_u32 v0, v2, v45, v0
	v_exp_f32_e32 v89, v18
	v_fmamk_f32 v18, v28, 0x3dd53b94, v52
	v_fmamk_f32 v19, v29, 0x3dd53b94, v52
	v_fmamk_f32 v20, v30, 0x3dd53b94, v52
	v_fmamk_f32 v21, v31, 0x3dd53b94, v52
	v_fmamk_f32 v22, v32, 0x3dd53b94, v52
	v_fmamk_f32 v23, v33, 0x3dd53b94, v52
	v_lshl_or_b32 v0, v0, 11, v41
	v_exp_f32_e32 v90, v18
	v_exp_f32_e32 v91, v19
	v_add_u32_e32 v2, v0, v42
	v_exp_f32_e32 v92, v20
	v_exp_f32_e32 v93, v21
	v_exp_f32_e32 v94, v22
	v_exp_f32_e32 v95, v23
	v_pk_fma_f32 v[202:203], v[14:15], s[52:53], v[52:53] op_sel_hi:[1,0,0]
	v_ashrrev_i32_e32 v3, 31, v2
	v_mov_b32_e32 v14, v1
	v_mov_b32_e32 v15, v1
	v_pk_fma_f32 v[200:201], v[16:17], s[52:53], v[52:53] op_sel_hi:[1,0,0]
	v_pk_fma_f32 v[204:205], v[12:13], s[52:53], v[52:53] op_sel_hi:[1,0,0]
	v_pk_fma_f32 v[206:207], v[10:11], s[52:53], v[52:53] op_sel_hi:[1,0,0]
	v_pk_fma_f32 v[208:209], v[8:9], s[52:53], v[52:53] op_sel_hi:[1,0,0]
	v_pk_fma_f32 v[210:211], v[6:7], s[52:53], v[52:53] op_sel_hi:[1,0,0]
	v_pk_fma_f32 v[212:213], v[4:5], s[52:53], v[52:53] op_sel_hi:[1,0,0]
; __device__ __forceinline__ unsigned lds_addr(LAS unsigned char* p) { return (unsigned)(size_t)p; }
; __device__ __forceinline__ int v_rd_base(int lane) { return ((lane & 3) << 3) | (((lane >> 2) & 3) << 6) | (((lane >> 4) & 1) << 5) | (((lane >> 5) & 1) << 8); }
; __device__ __forceinline__ void attn_block(const Params& p, LAS unsigned char* lds, int h, int qb) {
;     ...
;     int ksrc[3], vsrc[2];
; #pragma unroll
;     for (int i = 0; i < 3; ++i) { const int j = i * 512 + tid, row = j / 24, cp = j % 24, c = (cp & ~7) | ((cp & 7) ^ ((row >> 1) & 7)); ksrc[i] = (row * KW + c * 8) * 2; }
; #pragma unroll
;     for (int i = 0; i < 2; ++i) { const int off = (i * 512 + tid) * 16, sub = off >> 9, rem = (off & 511) >> 1, kk = (sub >> 2) * 8 + (rem >> 5), c = (sub & 3) * 32 + (rem & 31);
;         const int k = (kk & ~0xC) | ((kk & 4) << 1) | ((kk & 8) >> 1); vsrc[i] = (k * VW + c) * 2; }
;     const int vb0 = (int)lds_addr(lds) + v_rd_base(lane);
;     const unsigned ldsw = (unsigned)wid * 1024u;
;     ...
;     float m_reg = -1e30f, l_reg = 0.f; f32x16 o[4];
; #pragma unroll
;     for (int j = 0; j < 4; ++j) o[j] = (f32x16){};
	v_lshl_add_u64 v[184:185], s[50:51], 0, v[2:3]
	v_lshl_add_u64 v[186:187], s[40:41], 0, v[34:35]
	v_lshl_add_u64 v[188:189], s[40:41], 0, v[36:37]
	v_lshl_add_u64 v[190:191], s[40:41], 0, v[38:39]
	v_mov_b32_e32 v0, v1
	v_mov_b32_e32 v2, v1
	v_mov_b32_e32 v3, v1
	v_mov_b32_e32 v4, v1
	v_mov_b32_e32 v5, v1
	v_mov_b32_e32 v6, v1
	v_mov_b32_e32 v7, v1
	v_mov_b32_e32 v8, v1
	v_mov_b32_e32 v9, v1
	v_mov_b32_e32 v10, v1
	v_mov_b32_e32 v11, v1
	v_mov_b32_e32 v12, v1
	v_mov_b32_e32 v13, v1
	v_mov_b64_e32 v[30:31], v[14:15]
	v_mov_b64_e32 v[46:47], v[14:15]
	v_mov_b64_e32 v[62:63], v[14:15]
	v_mov_b64_e32 v[78:79], v[14:15]
	v_add_u32_e32 v225, 0, v218
	v_mov_b32_e32 v230, 0
	s_mov_b32 s86, 1
	s_mov_b32 s85, 0x10000
	v_mov_b64_e32 v[28:29], v[12:13]
	v_mov_b64_e32 v[26:27], v[10:11]
	v_mov_b64_e32 v[24:25], v[8:9]
	v_mov_b64_e32 v[22:23], v[6:7]
	v_mov_b64_e32 v[20:21], v[4:5]
	v_mov_b64_e32 v[18:19], v[2:3]
	v_mov_b64_e32 v[16:17], v[0:1]
	v_mov_b64_e32 v[44:45], v[12:13]
	v_mov_b64_e32 v[42:43], v[10:11]
	v_mov_b64_e32 v[40:41], v[8:9]
	v_mov_b64_e32 v[38:39], v[6:7]
	v_mov_b64_e32 v[36:37], v[4:5]
	v_mov_b64_e32 v[34:35], v[2:3]
	v_mov_b64_e32 v[32:33], v[0:1]
	v_mov_b64_e32 v[60:61], v[12:13]
	v_mov_b64_e32 v[58:59], v[10:11]
	v_mov_b64_e32 v[56:57], v[8:9]
	v_mov_b64_e32 v[54:55], v[6:7]
	v_mov_b64_e32 v[52:53], v[4:5]
	v_mov_b64_e32 v[50:51], v[2:3]
	v_mov_b64_e32 v[48:49], v[0:1]
	v_mov_b64_e32 v[76:77], v[12:13]
	v_mov_b64_e32 v[74:75], v[10:11]
	v_mov_b64_e32 v[72:73], v[8:9]
	v_mov_b64_e32 v[70:71], v[6:7]
	v_mov_b64_e32 v[68:69], v[4:5]
	v_mov_b64_e32 v[66:67], v[2:3]
	v_mov_b64_e32 v[64:65], v[0:1]
	s_mov_b64 s[54:55], 0x2ba60000
	s_mov_b64 s[56:57], 0x2ea40000
	v_mul_u32_u24_e32 v4, 0xaab, v199
	v_lshrrev_b32_e32 v4, 16, v4
	v_mul_u32_u24_e32 v5, 24, v4
	v_sub_u32_e32 v5, v199, v5
	v_bfe_u32 v6, v4, 1, 3
	v_and_b32_e32 v7, 7, v5
	v_xor_b32_e32 v7, v7, v6
	v_and_or_b32 v7, v5, 24, v7
	v_mul_u32_u24_e32 v4, 0xc00, v4
	v_lshl_add_u32 v8, v7, 4, v4
	v_lshl_add_u64 v[10:11], s[14:15], 0, v[186:187]
	v_lshl_add_u64 v[10:11], v[10:11], 0, s[54:55]
	v_sub_co_u32_e64 v10, s[98:99], v10, v8
	s_nop 1
	v_subbrev_co_u32_e64 v11, s[98:99], 0, v11, s[98:99]
	v_lshrrev_b32_e32 v4, 7, v199
	v_bfe_u32 v5, v199, 2, 3
	v_lshl_or_b32 v4, v4, 3, v5
	v_and_b32_e32 v5, 0xfffffff3, v4
	v_and_b32_e32 v6, 4, v4
	v_lshl_or_b32 v5, v6, 1, v5
	v_and_b32_e32 v6, 8, v4
	v_lshrrev_b32_e32 v6, 1, v6
	v_or_b32_e32 v5, v5, v6
	v_bfe_u32 v6, v199, 5, 2
	v_and_b32_e32 v7, 3, v199
	v_lshlrev_b32_e32 v6, 6, v6
	v_lshl_or_b32 v6, v7, 4, v6
	v_lshl_add_u32 v9, v5, 11, v6
	v_lshl_add_u64 v[12:13], s[14:15], 0, v[182:183]
	v_lshl_add_u64 v[12:13], v[12:13], 0, s[56:57]
	v_sub_co_u32_e64 v12, s[98:99], v12, v9
	s_nop 1
	v_subbrev_co_u32_e64 v13, s[98:99], 0, v13, s[98:99]
	s_nop 1
	v_readfirstlane_b32 s54, v10
	v_readfirstlane_b32 s55, v11
	v_readfirstlane_b32 s56, v12
	v_readfirstlane_b32 s57, v13
	v_mul_u32_u24_e32 v4, 0xaab, v199
	v_lshrrev_b32_e32 v4, 16, v4
	v_mul_u32_u24_e32 v5, 24, v4
	v_sub_u32_e32 v5, v199, v5
	v_bfe_u32 v6, v4, 1, 3
	v_and_b32_e32 v7, 7, v5
	v_xor_b32_e32 v7, v7, v6
	v_and_or_b32 v7, v5, 24, v7
	v_mul_u32_u24_e32 v4, 0xc00, v4
	v_lshl_add_u32 v186, v7, 4, v4
	v_add_u32_e32 v3, 256, v199
	v_mul_u32_u24_e32 v4, 0xaab, v3
	v_lshrrev_b32_e32 v4, 16, v4
	v_mul_u32_u24_e32 v5, 24, v4
	v_sub_u32_e32 v5, v3, v5
	v_bfe_u32 v6, v4, 1, 3
	v_and_b32_e32 v7, 7, v5
	v_xor_b32_e32 v7, v7, v6
	v_and_or_b32 v7, v5, 24, v7
	v_mul_u32_u24_e32 v4, 0xc00, v4
	v_lshl_add_u32 v187, v7, 4, v4
	v_add_u32_e32 v3, 512, v199
	v_mul_u32_u24_e32 v4, 0xaab, v3
	v_lshrrev_b32_e32 v4, 16, v4
	v_mul_u32_u24_e32 v5, 24, v4
	v_sub_u32_e32 v5, v3, v5
	v_bfe_u32 v6, v4, 1, 3
	v_and_b32_e32 v7, 7, v5
	v_xor_b32_e32 v7, v7, v6
	v_and_or_b32 v7, v5, 24, v7
	v_mul_u32_u24_e32 v4, 0xc00, v4
	v_lshl_add_u32 v188, v7, 4, v4
	v_add_u32_e32 v3, 768, v199
	v_mul_u32_u24_e32 v4, 0xaab, v3
	v_lshrrev_b32_e32 v4, 16, v4
	v_mul_u32_u24_e32 v5, 24, v4
	v_sub_u32_e32 v5, v3, v5
	v_bfe_u32 v6, v4, 1, 3
	v_and_b32_e32 v7, 7, v5
	v_xor_b32_e32 v7, v7, v6
	v_and_or_b32 v7, v5, 24, v7
	v_mul_u32_u24_e32 v4, 0xc00, v4
	v_lshl_add_u32 v189, v7, 4, v4
	v_add_u32_e32 v3, 1024, v199
	v_mul_u32_u24_e32 v4, 0xaab, v3
	v_lshrrev_b32_e32 v4, 16, v4
	v_mul_u32_u24_e32 v5, 24, v4
	v_sub_u32_e32 v5, v3, v5
	v_bfe_u32 v6, v4, 1, 3
	v_and_b32_e32 v7, 7, v5
	v_xor_b32_e32 v7, v7, v6
	v_and_or_b32 v7, v5, 24, v7
	v_mul_u32_u24_e32 v4, 0xc00, v4
	v_lshl_add_u32 v190, v7, 4, v4
	v_add_u32_e32 v3, 1280, v199
	v_mul_u32_u24_e32 v4, 0xaab, v3
	v_lshrrev_b32_e32 v4, 16, v4
	v_mul_u32_u24_e32 v5, 24, v4
	v_sub_u32_e32 v5, v3, v5
	v_bfe_u32 v6, v4, 1, 3
	v_and_b32_e32 v7, 7, v5
	v_xor_b32_e32 v7, v7, v6
	v_and_or_b32 v7, v5, 24, v7
	v_mul_u32_u24_e32 v4, 0xc00, v4
	v_lshl_add_u32 v191, v7, 4, v4
	v_lshrrev_b32_e32 v4, 7, v199
	v_bfe_u32 v5, v199, 2, 3
	v_lshl_or_b32 v4, v4, 3, v5
	v_and_b32_e32 v5, 0xfffffff3, v4
	v_and_b32_e32 v6, 4, v4
	v_lshl_or_b32 v5, v6, 1, v5
	v_and_b32_e32 v6, 8, v4
	v_lshrrev_b32_e32 v6, 1, v6
	v_or_b32_e32 v5, v5, v6
	v_bfe_u32 v6, v199, 5, 2
	v_and_b32_e32 v7, 3, v199
	v_lshlrev_b32_e32 v6, 6, v6
	v_lshl_or_b32 v6, v7, 4, v6
	v_lshl_add_u32 v182, v5, 11, v6
	v_add_u32_e32 v3, 256, v199
	v_lshrrev_b32_e32 v4, 7, v3
	v_bfe_u32 v5, v3, 2, 3
	v_lshl_or_b32 v4, v4, 3, v5
	v_and_b32_e32 v5, 0xfffffff3, v4
	v_and_b32_e32 v6, 4, v4
	v_lshl_or_b32 v5, v6, 1, v5
	v_and_b32_e32 v6, 8, v4
	v_lshrrev_b32_e32 v6, 1, v6
	v_or_b32_e32 v5, v5, v6
	v_bfe_u32 v6, v3, 5, 2
	v_and_b32_e32 v7, 3, v3
	v_lshlrev_b32_e32 v6, 6, v6
	v_lshl_or_b32 v6, v7, 4, v6
	v_lshl_add_u32 v183, v5, 11, v6
	v_add_u32_e32 v3, 512, v199
	v_lshrrev_b32_e32 v4, 7, v3
	v_bfe_u32 v5, v3, 2, 3
	v_lshl_or_b32 v4, v4, 3, v5
	v_and_b32_e32 v5, 0xfffffff3, v4
	v_and_b32_e32 v6, 4, v4
	v_lshl_or_b32 v5, v6, 1, v5
	v_and_b32_e32 v6, 8, v4
	v_lshrrev_b32_e32 v6, 1, v6
	v_or_b32_e32 v5, v5, v6
	v_bfe_u32 v6, v3, 5, 2
	v_and_b32_e32 v7, 3, v3
	v_lshlrev_b32_e32 v6, 6, v6
	v_lshl_or_b32 v6, v7, 4, v6
	v_lshl_add_u32 v184, v5, 11, v6
	v_add_u32_e32 v3, 768, v199
	v_lshrrev_b32_e32 v4, 7, v3
	v_bfe_u32 v5, v3, 2, 3
	v_lshl_or_b32 v4, v4, 3, v5
	v_and_b32_e32 v5, 0xfffffff3, v4
	v_and_b32_e32 v6, 4, v4
	v_lshl_or_b32 v5, v6, 1, v5
	v_and_b32_e32 v6, 8, v4
	v_lshrrev_b32_e32 v6, 1, v6
	v_or_b32_e32 v5, v5, v6
	v_bfe_u32 v6, v3, 5, 2
	v_and_b32_e32 v7, 3, v3
	v_lshlrev_b32_e32 v6, 6, v6
	v_lshl_or_b32 v6, v7, 4, v6
	v_lshl_add_u32 v185, v5, 11, v6
	s_nop 4
.LBB0_326:
	s_add_i32 s34, s86, 1
	s_cmp_lt_i32 s34, s80
	s_cselect_b64 s[82:83], -1, 0
	s_cmp_ge_i32 s34, s80
	s_cbranch_scc1 .LBB0_328
	s_cmp_lg_u32 s100, 0
	s_cbranch_scc1 .LBB0_328
	s_add_i32 m0, s17, 0x10000
	s_add_i32 s34, s85, 0xffff8000
	global_load_lds_dwordx4 v186, s[54:55]
	s_add_i32 m0, s17, 0x11000
	s_and_b32 s34, s34, 0xc000
	global_load_lds_dwordx4 v187, s[54:55]
	s_add_i32 m0, s17, 0x12000
	s_add_i32 s34, s17, s34
	global_load_lds_dwordx4 v188, s[54:55]
	s_add_i32 m0, s17, 0x13000
	s_nop 0
	global_load_lds_dwordx4 v189, s[54:55]
	s_add_i32 m0, s17, 0x14000
	s_nop 0
	global_load_lds_dwordx4 v190, s[54:55]
	s_add_i32 m0, s17, 0x15000
	s_nop 0
	global_load_lds_dwordx4 v191, s[54:55]
	s_mov_b32 m0, s34
	s_nop 0
	global_load_lds_dwordx4 v182, s[56:57]
	s_add_i32 m0, s34, 0x1000
	s_nop 0
	global_load_lds_dwordx4 v183, s[56:57]
	s_add_i32 m0, s34, 0x2000
	s_nop 0
	global_load_lds_dwordx4 v184, s[56:57]
	s_add_i32 m0, s34, 0x3000
	s_nop 0
	global_load_lds_dwordx4 v185, s[56:57]
	s_add_u32 s54, s54, 0x30000
	s_addc_u32 s55, s55, 0
	s_add_u32 s56, s56, 0x20000
	s_addc_u32 s57, s57, 0

; #define SBAR() __builtin_amdgcn_sched_barrier(0)
; #define PV_RD(F_, d0) do { constexpr int b_ = V_OFF + v_rd_off(d0, 0, 0); \
;         TRRD(F_[0], b_); TRRD(F_[1], b_ + 2048); TRRD(F_[2], b_ + 4096); TRRD(F_[3], b_ + 6144); TRRD(F_[4], b_ + 8192); TRRD(F_[5], b_ + 10240); TRRD(F_[6], b_ + 12288); TRRD(F_[7], b_ + 14336); } while (0)
; template <int k> __device__ __forceinline__ void par_snip(f32x16& p0, f32x16& p1, float& m_reg, float& pmax, float& alpha, float& mnL, float msk) {
;     constexpr float C2 = 1.4426950408889634f * SCALE;
;     if constexpr (k < 4) { constexpr int j = 4 * k; const float a = fmaxf(fmaxf(p0[j], p0[j + 1]), fmaxf(p0[j + 2], p0[j + 3])), b = fmaxf(fmaxf(p1[j], p1[j + 1]), fmaxf(p1[j + 2], p1[j + 3]));
;         pmax = (k == 0) ? fmaxf(a, b) : fmaxf(pmax, fmaxf(a, b)); }
;     else if constexpr (k == 4) { pmax += msk;
;         { auto rr = __builtin_amdgcn_permlane32_swap(__float_as_uint(pmax), __float_as_uint(pmax), false, false); pmax = fmaxf(__uint_as_float(rr[0]), __uint_as_float(rr[1])); }
;         const bool defer = __all((pmax - m_reg) * SCALE <= THR);
;         const float mn = defer ? m_reg : fmaxf(m_reg, pmax);
;         alpha = __builtin_amdgcn_exp2f((m_reg - mn) * C2); m_reg = mn; mnL = fmaf(-mn, C2, msk); }
;     else if constexpr (k < 9) { constexpr int j = 4 * (k - 5);
; #pragma unroll
;         for (int e = 0; e < 4; ++e) { p0[j + e] = fmaf(p0[j + e], C2, mnL); p1[j + e] = fmaf(p1[j + e], C2, mnL); } }
;     else if constexpr (k < 15) { constexpr int j = 2 * (k - 9); p0[j] = __builtin_amdgcn_exp2f(p0[j]); p0[j + 1] = __builtin_amdgcn_exp2f(p0[j + 1]); }
;     else if constexpr (k == 15) {
; #pragma unroll
;         for (int e = 12; e < 16; ++e) p0[e] = __builtin_amdgcn_exp2f(p0[e]); }
; }
; __device__ __forceinline__ void stage_pv_par(f32x16* o, int vb0, bf16x8 pa0, bf16x8 pa1, bf16x8 pa2, bf16x8 pa3,
;                                              f32x16& x0, f32x16& x1, float& m_reg, float& alpha, float msk) {
;     ...
;     float pmax = 0.f, mnL = 0.f; s16x4 fA[8];
;     SBAR(); PV_RD(fA, 0); PV_WAIT(fA, 0); SBAR();
;     PVS(fA, 0); PV_RD(fA, 1); PV_WAIT(fA, 0); SBAR();
;     PVS(fA, 1); PV_RD(fA, 2); PV_WAIT(fA, 0); SBAR();
;     PVS(fA, 2); PV_RD(fA, 3); PV_WAIT(fA, 0); SBAR();
;     PVS(fA, 3);
.Lmy_mid_a:
	s_and_b32 s34, s85, 0xc000
	v_add_u32_e32 v217, s34, v225
	ds_read_b64_tr_b16 v[194:195], v217 offset:0
	ds_read_b64_tr_b16 v[196:197], v217 offset:0x800
	ds_read_b64_tr_b16 v[200:201], v217 offset:0x1000
	ds_read_b64_tr_b16 v[202:203], v217 offset:0x1800
	ds_read_b64_tr_b16 v[204:205], v217 offset:0x2000
	ds_read_b64_tr_b16 v[206:207], v217 offset:0x2800
	ds_read_b64_tr_b16 v[208:209], v217 offset:0x3000
	ds_read_b64_tr_b16 v[210:211], v217 offset:0x3800
	s_nop 0
	s_waitcnt lgkmcnt(0)
	s_nop 0
	v_mfma_f32_32x32x16_bf16 v[64:79], v[194:197], v[2:5], v[64:79]
	s_nop 5
	v_max3_f32 v0, v96, v97, v98
	v_max3_f32 v194, v112, v113, v114
	v_max3_f32 v0, v0, v99, v100
	v_max3_f32 v194, v194, v115, v116
	v_mfma_f32_32x32x16_bf16 v[64:79], v[200:203], v[6:9], v[64:79]
	v_max3_f32 v0, v0, v101, v102
	v_max3_f32 v194, v194, v117, v118
	v_max3_f32 v0, v0, v103, v104
	v_max3_f32 v194, v194, v119, v120
	v_mfma_f32_32x32x16_bf16 v[64:79], v[204:207], v[10:13], v[64:79]
	v_max3_f32 v0, v0, v105, v106
	v_max3_f32 v194, v194, v121, v122
	v_max3_f32 v0, v0, v107, v108
	v_max3_f32 v194, v194, v123, v124
	v_mfma_f32_32x32x16_bf16 v[64:79], v[208:211], v[176:179], v[64:79]
	v_max3_f32 v0, v0, v109, v110
	v_max3_f32 v194, v194, v125, v126
	v_max3_f32 v0, v0, v111, v127
	v_max_f32_e32 v0, v0, v194
	ds_read_b64_tr_b16 v[194:195], v217 offset:0x200
	ds_read_b64_tr_b16 v[196:197], v217 offset:0xa00
	ds_read_b64_tr_b16 v[200:201], v217 offset:0x1200
	ds_read_b64_tr_b16 v[202:203], v217 offset:0x1a00
	ds_read_b64_tr_b16 v[204:205], v217 offset:0x2200
	ds_read_b64_tr_b16 v[206:207], v217 offset:0x2a00
	ds_read_b64_tr_b16 v[208:209], v217 offset:0x3200
	ds_read_b64_tr_b16 v[210:211], v217 offset:0x3a00
	s_nop 0
	s_waitcnt lgkmcnt(0)
	v_add_f32_e32 v0, v216, v0
	v_mfma_f32_32x32x16_bf16 v[48:63], v[194:197], v[2:5], v[48:63]
	v_mov_b32_e32 v194, v0
	s_nop 1
	v_permlane32_swap_b32_e32 v0, v194
	v_max_f32_e32 v0, v0, v194
	v_sub_f32_e32 v194, v0, v244
	v_mul_f32_e32 v194, 0x3d93cd3a, v194
	v_cmp_ge_f32_e32 vcc, s63, v194
	s_cmp_eq_u64 vcc, exec
	s_cselect_b64 vcc, -1, 0
	v_max_f32_e32 v0, v244, v0
	v_cndmask_b32_e32 v246, v0, v244, vcc
	v_sub_f32_e32 v0, v244, v246
	v_mul_f32_e32 v0, 0x3dd53b94, v0
	v_exp_f32_e32 v0, v0
	v_fmac_f32_e32 v216, 0xbdd53b94, v246
	v_mfma_f32_32x32x16_bf16 v[48:63], v[200:203], v[6:9], v[48:63]
	v_fmamk_f32 v96, v96, 0x3dd53b94, v216
	v_fmamk_f32 v97, v97, 0x3dd53b94, v216
	v_fmamk_f32 v98, v98, 0x3dd53b94, v216
	v_fmamk_f32 v99, v99, 0x3dd53b94, v216
	v_exp_f32_e32 v243, v96
	v_mfma_f32_32x32x16_bf16 v[48:63], v[204:207], v[10:13], v[48:63]
	v_fmamk_f32 v100, v100, 0x3dd53b94, v216
	v_fmamk_f32 v101, v101, 0x3dd53b94, v216
	v_exp_f32_e32 v242, v97
	v_exp_f32_e32 v241, v98
	v_mfma_f32_32x32x16_bf16 v[48:63], v[208:211], v[176:179], v[48:63]
	v_fmamk_f32 v102, v102, 0x3dd53b94, v216
	v_fmamk_f32 v103, v103, 0x3dd53b94, v216
	v_exp_f32_e32 v240, v99
	v_exp_f32_e32 v239, v100
	ds_read_b64_tr_b16 v[194:195], v217 offset:0x400
	ds_read_b64_tr_b16 v[196:197], v217 offset:0xc00
	ds_read_b64_tr_b16 v[200:201], v217 offset:0x1400
	ds_read_b64_tr_b16 v[202:203], v217 offset:0x1c00
	ds_read_b64_tr_b16 v[204:205], v217 offset:0x2400
	ds_read_b64_tr_b16 v[206:207], v217 offset:0x2c00
	ds_read_b64_tr_b16 v[208:209], v217 offset:0x3400
	ds_read_b64_tr_b16 v[210:211], v217 offset:0x3c00
	s_nop 0
	s_waitcnt lgkmcnt(0)
	s_nop 0
	v_mfma_f32_32x32x16_bf16 v[32:47], v[194:197], v[2:5], v[32:47]
	v_fmamk_f32 v104, v104, 0x3dd53b94, v216
	v_fmamk_f32 v105, v105, 0x3dd53b94, v216
	v_exp_f32_e32 v238, v101
	v_exp_f32_e32 v237, v102
	v_mfma_f32_32x32x16_bf16 v[32:47], v[200:203], v[6:9], v[32:47]
	v_fmamk_f32 v106, v106, 0x3dd53b94, v216
	v_fmamk_f32 v107, v107, 0x3dd53b94, v216
	v_exp_f32_e32 v236, v103
	v_exp_f32_e32 v235, v104
	v_mfma_f32_32x32x16_bf16 v[32:47], v[204:207], v[10:13], v[32:47]
	v_fmamk_f32 v108, v108, 0x3dd53b94, v216
	v_fmamk_f32 v109, v109, 0x3dd53b94, v216
	v_exp_f32_e32 v234, v105
	v_exp_f32_e32 v233, v106
	v_mfma_f32_32x32x16_bf16 v[32:47], v[208:211], v[176:179], v[32:47]
	v_fmamk_f32 v110, v110, 0x3dd53b94, v216
	v_fmamk_f32 v111, v111, 0x3dd53b94, v216
	v_exp_f32_e32 v232, v107
	v_exp_f32_e32 v231, v108
	ds_read_b64_tr_b16 v[194:195], v217 offset:0x600
	ds_read_b64_tr_b16 v[196:197], v217 offset:0xe00
	ds_read_b64_tr_b16 v[200:201], v217 offset:0x1600
	ds_read_b64_tr_b16 v[202:203], v217 offset:0x1e00
	ds_read_b64_tr_b16 v[204:205], v217 offset:0x2600
	ds_read_b64_tr_b16 v[206:207], v217 offset:0x2e00
	ds_read_b64_tr_b16 v[208:209], v217 offset:0x3600
	ds_read_b64_tr_b16 v[210:211], v217 offset:0x3e00
	s_nop 0
	s_waitcnt lgkmcnt(0)
	s_nop 0
	v_mfma_f32_32x32x16_bf16 v[16:31], v[194:197], v[2:5], v[16:31]
	v_exp_f32_e32 v230, v109
	v_fmamk_f32 v14, v112, 0x3dd53b94, v216
	v_fmamk_f32 v15, v113, 0x3dd53b94, v216
	v_fmamk_f32 v116, v116, 0x3dd53b94, v216
	v_fmamk_f32 v117, v117, 0x3dd53b94, v216
	v_mfma_f32_32x32x16_bf16 v[16:31], v[200:203], v[6:9], v[16:31]
	v_fmamk_f32 v118, v118, 0x3dd53b94, v216
	v_fmamk_f32 v119, v119, 0x3dd53b94, v216
	v_fmamk_f32 v120, v120, 0x3dd53b94, v216
	v_fmamk_f32 v121, v121, 0x3dd53b94, v216
	v_fmamk_f32 v122, v122, 0x3dd53b94, v216
	v_fmamk_f32 v123, v123, 0x3dd53b94, v216
	v_mfma_f32_32x32x16_bf16 v[16:31], v[204:207], v[10:13], v[16:31]
	v_fmamk_f32 v124, v124, 0x3dd53b94, v216
	v_fmamk_f32 v125, v125, 0x3dd53b94, v216
	v_fmamk_f32 v126, v126, 0x3dd53b94, v216
	v_fmamk_f32 v127, v127, 0x3dd53b94, v216
	v_mfma_f32_32x32x16_bf16 v[16:31], v[208:211], v[176:179], v[16:31]
	v_cmp_gt_f32_e32 vcc, 1.0, v0
	s_cbranch_vccz .LBB0_330
	v_pk_mul_f32 v[78:79], v[78:79], v[0:1] op_sel_hi:[1,0]
	v_pk_mul_f32 v[76:77], v[76:77], v[0:1] op_sel_hi:[1,0]
	v_pk_mul_f32 v[74:75], v[74:75], v[0:1] op_sel_hi:[1,0]
	v_pk_mul_f32 v[72:73], v[72:73], v[0:1] op_sel_hi:[1,0]
	v_pk_mul_f32 v[70:71], v[70:71], v[0:1] op_sel_hi:[1,0]
	v_pk_mul_f32 v[68:69], v[68:69], v[0:1] op_sel_hi:[1,0]
	v_pk_mul_f32 v[66:67], v[66:67], v[0:1] op_sel_hi:[1,0]
	v_pk_mul_f32 v[64:65], v[64:65], v[0:1] op_sel_hi:[1,0]
	v_pk_mul_f32 v[62:63], v[0:1], v[62:63] op_sel_hi:[0,1]
	v_pk_mul_f32 v[60:61], v[0:1], v[60:61] op_sel_hi:[0,1]
	v_pk_mul_f32 v[58:59], v[0:1], v[58:59] op_sel_hi:[0,1]
	v_pk_mul_f32 v[56:57], v[0:1], v[56:57] op_sel_hi:[0,1]
	v_pk_mul_f32 v[54:55], v[0:1], v[54:55] op_sel_hi:[0,1]
	v_pk_mul_f32 v[52:53], v[0:1], v[52:53] op_sel_hi:[0,1]
	v_pk_mul_f32 v[50:51], v[0:1], v[50:51] op_sel_hi:[0,1]
	v_pk_mul_f32 v[48:49], v[0:1], v[48:49] op_sel_hi:[0,1]
	v_pk_mul_f32 v[46:47], v[0:1], v[46:47] op_sel_hi:[0,1]
	v_pk_mul_f32 v[44:45], v[0:1], v[44:45] op_sel_hi:[0,1]
	v_pk_mul_f32 v[42:43], v[0:1], v[42:43] op_sel_hi:[0,1]
	v_pk_mul_f32 v[40:41], v[0:1], v[40:41] op_sel_hi:[0,1]
	v_pk_mul_f32 v[38:39], v[0:1], v[38:39] op_sel_hi:[0,1]
	v_pk_mul_f32 v[36:37], v[0:1], v[36:37] op_sel_hi:[0,1]
	v_pk_mul_f32 v[34:35], v[0:1], v[34:35] op_sel_hi:[0,1]
	v_pk_mul_f32 v[32:33], v[0:1], v[32:33] op_sel_hi:[0,1]
	v_pk_mul_f32 v[30:31], v[0:1], v[30:31] op_sel_hi:[0,1]
	v_pk_mul_f32 v[28:29], v[0:1], v[28:29] op_sel_hi:[0,1]
	v_pk_mul_f32 v[26:27], v[0:1], v[26:27] op_sel_hi:[0,1]
	v_pk_mul_f32 v[24:25], v[0:1], v[24:25] op_sel_hi:[0,1]
	v_pk_mul_f32 v[22:23], v[0:1], v[22:23] op_sel_hi:[0,1]
	v_pk_mul_f32 v[20:21], v[0:1], v[20:21] op_sel_hi:[0,1]
	v_pk_mul_f32 v[18:19], v[0:1], v[18:19] op_sel_hi:[0,1]
	v_pk_mul_f32 v[16:17], v[0:1], v[16:17] op_sel_hi:[0,1]

.Lmy_end_a:
	s_cbranch_vccnz .LBB0_336
	s_cmp_ge_i32 s82, s80
	s_cbranch_scc1 .LBB0_333
	s_cmp_lg_u32 s100, 0
	s_cbranch_scc1 .LBB0_333
	s_add_i32 m0, s17, 0x16000
	s_add_i32 s34, s85, 0xffffc000
	global_load_lds_dwordx4 v186, s[54:55]
	s_add_i32 m0, s17, 0x17000
	s_and_b32 s34, s34, 0xc000
	global_load_lds_dwordx4 v187, s[54:55]
	s_add_i32 m0, s17, 0x18000
	s_add_i32 s34, s17, s34
	global_load_lds_dwordx4 v188, s[54:55]
	s_add_i32 m0, s17, 0x19000
	s_nop 0
	global_load_lds_dwordx4 v189, s[54:55]
	s_add_i32 m0, s17, 0x1a000
	s_nop 0
	global_load_lds_dwordx4 v190, s[54:55]
	s_add_i32 m0, s17, 0x1b000
	s_nop 0
	global_load_lds_dwordx4 v191, s[54:55]
	s_mov_b32 m0, s34
	s_nop 0
	global_load_lds_dwordx4 v182, s[56:57]
	s_add_i32 m0, s34, 0x1000
	s_nop 0
	global_load_lds_dwordx4 v183, s[56:57]
	s_add_i32 m0, s34, 0x2000
	s_nop 0
	global_load_lds_dwordx4 v184, s[56:57]
	s_add_i32 m0, s34, 0x3000
	s_nop 0
	global_load_lds_dwordx4 v185, s[56:57]
	s_add_u32 s54, s54, 0x30000
	s_addc_u32 s55, s55, 0
	s_add_u32 s56, s56, 0x20000
	s_addc_u32 s57, s57, 0

; #define SBAR() __builtin_amdgcn_sched_barrier(0)
; #define PV_RD(F_, d0) do { constexpr int b_ = V_OFF + v_rd_off(d0, 0, 0); \
;         TRRD(F_[0], b_); TRRD(F_[1], b_ + 2048); TRRD(F_[2], b_ + 4096); TRRD(F_[3], b_ + 6144); TRRD(F_[4], b_ + 8192); TRRD(F_[5], b_ + 10240); TRRD(F_[6], b_ + 12288); TRRD(F_[7], b_ + 14336); } while (0)
; template <int k> __device__ __forceinline__ void par_snip(f32x16& p0, f32x16& p1, float& m_reg, float& pmax, float& alpha, float& mnL, float msk) {
;     constexpr float C2 = 1.4426950408889634f * SCALE;
;     if constexpr (k < 4) { constexpr int j = 4 * k; const float a = fmaxf(fmaxf(p0[j], p0[j + 1]), fmaxf(p0[j + 2], p0[j + 3])), b = fmaxf(fmaxf(p1[j], p1[j + 1]), fmaxf(p1[j + 2], p1[j + 3]));
;         pmax = (k == 0) ? fmaxf(a, b) : fmaxf(pmax, fmaxf(a, b)); }
;     else if constexpr (k == 4) { pmax += msk;
;         { auto rr = __builtin_amdgcn_permlane32_swap(__float_as_uint(pmax), __float_as_uint(pmax), false, false); pmax = fmaxf(__uint_as_float(rr[0]), __uint_as_float(rr[1])); }
;         const bool defer = __all((pmax - m_reg) * SCALE <= THR);
;         const float mn = defer ? m_reg : fmaxf(m_reg, pmax);
;         alpha = __builtin_amdgcn_exp2f((m_reg - mn) * C2); m_reg = mn; mnL = fmaf(-mn, C2, msk); }
;     else if constexpr (k < 9) { constexpr int j = 4 * (k - 5);
; #pragma unroll
;         for (int e = 0; e < 4; ++e) { p0[j + e] = fmaf(p0[j + e], C2, mnL); p1[j + e] = fmaf(p1[j + e], C2, mnL); } }
;     else if constexpr (k < 15) { constexpr int j = 2 * (k - 9); p0[j] = __builtin_amdgcn_exp2f(p0[j]); p0[j + 1] = __builtin_amdgcn_exp2f(p0[j + 1]); }
;     else if constexpr (k == 15) {
; #pragma unroll
;         for (int e = 12; e < 16; ++e) p0[e] = __builtin_amdgcn_exp2f(p0[e]); }
; }
; __device__ __forceinline__ void stage_pv_par(f32x16* o, int vb0, bf16x8 pa0, bf16x8 pa1, bf16x8 pa2, bf16x8 pa3,
;                                              f32x16& x0, f32x16& x1, float& m_reg, float& alpha, float msk) {
;     ...
;     float pmax = 0.f, mnL = 0.f; s16x4 fA[8];
;     SBAR(); PV_RD(fA, 0); PV_WAIT(fA, 0); SBAR();
;     PVS(fA, 0); PV_RD(fA, 1); PV_WAIT(fA, 0); SBAR();
;     PVS(fA, 1); PV_RD(fA, 2); PV_WAIT(fA, 0); SBAR();
;     PVS(fA, 2); PV_RD(fA, 3); PV_WAIT(fA, 0); SBAR();
;     PVS(fA, 3);
.Lmy_mid_b:
	s_and_b32 s34, s34, 0xc000
	v_add_u32_e32 v217, s34, v225
	ds_read_b64_tr_b16 v[194:195], v217 offset:0
	ds_read_b64_tr_b16 v[196:197], v217 offset:0x800
	ds_read_b64_tr_b16 v[232:233], v217 offset:0x1000
	ds_read_b64_tr_b16 v[234:235], v217 offset:0x1800
	ds_read_b64_tr_b16 v[236:237], v217 offset:0x2000
	ds_read_b64_tr_b16 v[238:239], v217 offset:0x2800
	ds_read_b64_tr_b16 v[240:241], v217 offset:0x3000
	ds_read_b64_tr_b16 v[242:243], v217 offset:0x3800
	s_nop 0
	s_waitcnt lgkmcnt(0)
	s_nop 0
	v_mfma_f32_32x32x16_bf16 v[64:79], v[194:197], v[2:5], v[64:79]
	s_nop 5
	v_max3_f32 v192, v96, v97, v98
	v_max3_f32 v194, v80, v81, v82
	v_max3_f32 v192, v192, v99, v100
	v_max3_f32 v194, v194, v83, v84
	v_mfma_f32_32x32x16_bf16 v[64:79], v[232:235], v[6:9], v[64:79]
	v_max3_f32 v192, v192, v101, v102
	v_max3_f32 v194, v194, v85, v86
	v_max3_f32 v192, v192, v103, v104
	v_max3_f32 v194, v194, v87, v88
	v_mfma_f32_32x32x16_bf16 v[64:79], v[236:239], v[10:13], v[64:79]
	v_max3_f32 v192, v192, v105, v106
	v_max3_f32 v194, v194, v89, v90
	v_max3_f32 v192, v192, v107, v108
	v_max3_f32 v194, v194, v91, v92
	v_mfma_f32_32x32x16_bf16 v[64:79], v[240:243], v[112:115], v[64:79]
	v_max3_f32 v192, v192, v109, v110
	v_max3_f32 v194, v194, v93, v94
	v_max3_f32 v192, v192, v111, v95
	v_max_f32_e32 v192, v192, v194
	ds_read_b64_tr_b16 v[194:195], v217 offset:0x200
	ds_read_b64_tr_b16 v[196:197], v217 offset:0xa00
	ds_read_b64_tr_b16 v[232:233], v217 offset:0x1200
	ds_read_b64_tr_b16 v[234:235], v217 offset:0x1a00
	ds_read_b64_tr_b16 v[236:237], v217 offset:0x2200
	ds_read_b64_tr_b16 v[238:239], v217 offset:0x2a00
	ds_read_b64_tr_b16 v[240:241], v217 offset:0x3200
	ds_read_b64_tr_b16 v[242:243], v217 offset:0x3a00
	s_nop 0
	s_waitcnt lgkmcnt(0)
	v_add_f32_e32 v192, v178, v192
	v_mfma_f32_32x32x16_bf16 v[48:63], v[194:197], v[2:5], v[48:63]
	v_mov_b32_e32 v194, v192
	s_nop 1
	v_permlane32_swap_b32_e32 v192, v194
	v_max_f32_e32 v192, v192, v194
	v_sub_f32_e32 v194, v192, v246
	v_mul_f32_e32 v194, 0x3d93cd3a, v194
	v_cmp_ge_f32_e32 vcc, s63, v194
	s_cmp_eq_u64 vcc, exec
	s_cselect_b64 vcc, -1, 0
	v_max_f32_e32 v192, v246, v192
	v_cndmask_b32_e32 v244, v192, v246, vcc
	v_sub_f32_e32 v192, v246, v244
	v_mul_f32_e32 v192, 0x3dd53b94, v192
	v_exp_f32_e32 v192, v192
	v_fmac_f32_e32 v178, 0xbdd53b94, v244
	v_mfma_f32_32x32x16_bf16 v[48:63], v[232:235], v[6:9], v[48:63]
	v_fmamk_f32 v214, v80, 0x3dd53b94, v178
	v_fmamk_f32 v215, v81, 0x3dd53b94, v178
	v_fmamk_f32 v212, v82, 0x3dd53b94, v178
	v_fmamk_f32 v213, v83, 0x3dd53b94, v178
	v_fmamk_f32 v210, v84, 0x3dd53b94, v178
	v_fmamk_f32 v211, v85, 0x3dd53b94, v178
	v_mfma_f32_32x32x16_bf16 v[48:63], v[236:239], v[10:13], v[48:63]
	v_fmamk_f32 v208, v86, 0x3dd53b94, v178
	v_fmamk_f32 v209, v87, 0x3dd53b94, v178
	v_fmamk_f32 v206, v88, 0x3dd53b94, v178
	v_fmamk_f32 v207, v89, 0x3dd53b94, v178
	v_fmamk_f32 v204, v90, 0x3dd53b94, v178
	v_fmamk_f32 v205, v91, 0x3dd53b94, v178
	v_mfma_f32_32x32x16_bf16 v[48:63], v[240:243], v[112:115], v[48:63]
	v_fmamk_f32 v202, v92, 0x3dd53b94, v178
	v_fmamk_f32 v203, v93, 0x3dd53b94, v178
	v_fmamk_f32 v200, v94, 0x3dd53b94, v178
	v_fmamk_f32 v201, v95, 0x3dd53b94, v178
	v_fmamk_f32 v96, v96, 0x3dd53b94, v178
	v_fmamk_f32 v97, v97, 0x3dd53b94, v178
	ds_read_b64_tr_b16 v[194:195], v217 offset:0x400
	ds_read_b64_tr_b16 v[196:197], v217 offset:0xc00
	ds_read_b64_tr_b16 v[232:233], v217 offset:0x1400
	ds_read_b64_tr_b16 v[234:235], v217 offset:0x1c00
	ds_read_b64_tr_b16 v[236:237], v217 offset:0x2400
	ds_read_b64_tr_b16 v[238:239], v217 offset:0x2c00
	ds_read_b64_tr_b16 v[240:241], v217 offset:0x3400
	ds_read_b64_tr_b16 v[242:243], v217 offset:0x3c00
	s_nop 0
	s_waitcnt lgkmcnt(0)
	s_nop 0
	v_mfma_f32_32x32x16_bf16 v[32:47], v[194:197], v[2:5], v[32:47]
	v_fmamk_f32 v98, v98, 0x3dd53b94, v178
	v_fmamk_f32 v99, v99, 0x3dd53b94, v178
	v_exp_f32_e32 v80, v96
	v_exp_f32_e32 v81, v97
	v_mfma_f32_32x32x16_bf16 v[32:47], v[232:235], v[6:9], v[32:47]
	v_fmamk_f32 v100, v100, 0x3dd53b94, v178
	v_fmamk_f32 v101, v101, 0x3dd53b94, v178
	v_exp_f32_e32 v82, v98
	v_exp_f32_e32 v83, v99
	v_mfma_f32_32x32x16_bf16 v[32:47], v[236:239], v[10:13], v[32:47]
	v_fmamk_f32 v102, v102, 0x3dd53b94, v178
	v_fmamk_f32 v103, v103, 0x3dd53b94, v178
	v_exp_f32_e32 v84, v100
	v_exp_f32_e32 v85, v101
	v_mfma_f32_32x32x16_bf16 v[32:47], v[240:243], v[112:115], v[32:47]
	v_fmamk_f32 v104, v104, 0x3dd53b94, v178
	v_fmamk_f32 v105, v105, 0x3dd53b94, v178
	v_exp_f32_e32 v86, v102
	v_exp_f32_e32 v87, v103
	ds_read_b64_tr_b16 v[194:195], v217 offset:0x600
	ds_read_b64_tr_b16 v[196:197], v217 offset:0xe00
	ds_read_b64_tr_b16 v[232:233], v217 offset:0x1600
	ds_read_b64_tr_b16 v[234:235], v217 offset:0x1e00
	ds_read_b64_tr_b16 v[236:237], v217 offset:0x2600
	ds_read_b64_tr_b16 v[238:239], v217 offset:0x2e00
	ds_read_b64_tr_b16 v[240:241], v217 offset:0x3600
	ds_read_b64_tr_b16 v[242:243], v217 offset:0x3e00
	s_nop 0
	s_waitcnt lgkmcnt(0)
	s_nop 0
	v_mfma_f32_32x32x16_bf16 v[16:31], v[194:197], v[2:5], v[16:31]
	v_fmamk_f32 v106, v106, 0x3dd53b94, v178
	v_fmamk_f32 v107, v107, 0x3dd53b94, v178
	v_exp_f32_e32 v88, v104
	v_exp_f32_e32 v89, v105
	v_mfma_f32_32x32x16_bf16 v[16:31], v[232:235], v[6:9], v[16:31]
	v_fmamk_f32 v108, v108, 0x3dd53b94, v178
	v_fmamk_f32 v109, v109, 0x3dd53b94, v178
	v_exp_f32_e32 v90, v106
	v_exp_f32_e32 v91, v107
	v_mfma_f32_32x32x16_bf16 v[16:31], v[236:239], v[10:13], v[16:31]
	v_fmamk_f32 v110, v110, 0x3dd53b94, v178
	v_fmamk_f32 v111, v111, 0x3dd53b94, v178
	v_exp_f32_e32 v92, v108
	v_exp_f32_e32 v93, v109
	v_mfma_f32_32x32x16_bf16 v[16:31], v[240:243], v[112:115], v[16:31]
	v_cmp_gt_f32_e32 vcc, 1.0, v192
	s_cbranch_vccz .LBB0_335
	v_pk_mul_f32 v[78:79], v[78:79], v[192:193] op_sel_hi:[1,0]
	v_pk_mul_f32 v[76:77], v[76:77], v[192:193] op_sel_hi:[1,0]
	v_pk_mul_f32 v[74:75], v[74:75], v[192:193] op_sel_hi:[1,0]
	v_pk_mul_f32 v[72:73], v[72:73], v[192:193] op_sel_hi:[1,0]
	v_pk_mul_f32 v[70:71], v[70:71], v[192:193] op_sel_hi:[1,0]
	v_pk_mul_f32 v[68:69], v[68:69], v[192:193] op_sel_hi:[1,0]
	v_pk_mul_f32 v[66:67], v[66:67], v[192:193] op_sel_hi:[1,0]
	v_pk_mul_f32 v[64:65], v[64:65], v[192:193] op_sel_hi:[1,0]
	v_pk_mul_f32 v[62:63], v[192:193], v[62:63] op_sel_hi:[0,1]
	v_pk_mul_f32 v[60:61], v[192:193], v[60:61] op_sel_hi:[0,1]
	v_pk_mul_f32 v[58:59], v[192:193], v[58:59] op_sel_hi:[0,1]
	v_pk_mul_f32 v[56:57], v[192:193], v[56:57] op_sel_hi:[0,1]
	v_pk_mul_f32 v[54:55], v[192:193], v[54:55] op_sel_hi:[0,1]
	v_pk_mul_f32 v[52:53], v[192:193], v[52:53] op_sel_hi:[0,1]
	v_pk_mul_f32 v[50:51], v[192:193], v[50:51] op_sel_hi:[0,1]
	v_pk_mul_f32 v[48:49], v[192:193], v[48:49] op_sel_hi:[0,1]
	v_pk_mul_f32 v[46:47], v[192:193], v[46:47] op_sel_hi:[0,1]
	v_pk_mul_f32 v[44:45], v[192:193], v[44:45] op_sel_hi:[0,1]
	v_pk_mul_f32 v[42:43], v[192:193], v[42:43] op_sel_hi:[0,1]
	v_pk_mul_f32 v[40:41], v[192:193], v[40:41] op_sel_hi:[0,1]
	v_pk_mul_f32 v[38:39], v[192:193], v[38:39] op_sel_hi:[0,1]
	v_pk_mul_f32 v[36:37], v[192:193], v[36:37] op_sel_hi:[0,1]
	v_pk_mul_f32 v[34:35], v[192:193], v[34:35] op_sel_hi:[0,1]
	v_pk_mul_f32 v[32:33], v[192:193], v[32:33] op_sel_hi:[0,1]
	v_pk_mul_f32 v[30:31], v[192:193], v[30:31] op_sel_hi:[0,1]
	v_pk_mul_f32 v[28:29], v[192:193], v[28:29] op_sel_hi:[0,1]
	v_pk_mul_f32 v[26:27], v[192:193], v[26:27] op_sel_hi:[0,1]
	v_pk_mul_f32 v[24:25], v[192:193], v[24:25] op_sel_hi:[0,1]
	v_pk_mul_f32 v[22:23], v[192:193], v[22:23] op_sel_hi:[0,1]
	v_pk_mul_f32 v[20:21], v[192:193], v[20:21] op_sel_hi:[0,1]
	v_pk_mul_f32 v[18:19], v[192:193], v[18:19] op_sel_hi:[0,1]
	v_pk_mul_f32 v[16:17], v[192:193], v[16:17] op_sel_hi:[0,1]

; __device__ __forceinline__ void attn_block(const Params& p, LAS unsigned char* lds, int h, int qb) {
;     ...
;     for (int t = 1; t < ntiles; t += 2) {
;         STEP(t, pB0, pB1, mnB, alB, pA0, pA1, alA);
;         if (t + 1 < ntiles) STEP(t + 1, pA0, pA1, mnA, alA, pB0, pB1, alB);
;     }
.LBB0_337:
	s_add_i32 s85, s85, 0x8000
	s_cmp_ge_i32 s82, s80
	s_cbranch_scc1 .LBB0_322
	s_mov_b32 s86, s82
	v_mov_b32_e32 v230, v245
	s_branch .LBB0_326
